# speedup vs baseline: 1.0022x; 1.0022x over previous
; __device__ __forceinline__ float bflo(unsigned u) { return __uint_as_float(u << 16); }
; __device__ __forceinline__ float bfhi(unsigned u) { return __uint_as_float(u & 0xffff0000u); }
; #define EPI_FENCE(j) do { if ((j) == 0) asm volatile("" ::: "memory"); } while (0)
; #define LAUNDER(x) asm volatile("" : "+s"(x))
; template <int PASS>
; __device__ __forceinline__ void gemm3_pass(const Params& p, int wid_s, char* shm) {
;     ...
;     int brow_l = brow; LAUNDER(brow_l); LAUNDER(pn); { int l2 = lane_id_v(); fr = l2 & 15; fq = l2 >> 4; }
;     const int tokbase = brow_l + wr * 64 + fq * 4;
;     const int cb = pn * 256 + wc * 64 + 4 * fr;
; #pragma unroll
;     for (int ai = 0; ai < 2; ++ai)
; #pragma unroll
;       for (int m = 0; m < 4; ++m)
; #pragma unroll
;         for (int j = 0; j < 4; ++j) { EPI_FENCE(j);
;           int tok = tokbase + ai * 128 + m * 16 + j;
;           uint2 g = *(const uint2*)(G + (size_t)tok * 4096 + (PASS == 0 ? 0 : 2048) + cb);
;           float o0 = bflo(g.x) * acc[ai][0][m][0][j], o1 = bfhi(g.x) * acc[ai][0][m][1][j];
;           float o2 = bflo(g.y) * acc[ai][1][m][0][j], o3 = bfhi(g.y) * acc[ai][1][m][1][j];
;           if (PASS == 1) {
;             uint2 pv = *(const uint2*)(MP + (size_t)tok * 2048 + cb);
;             o0 += bflo(pv.x); o1 += bfhi(pv.x); o2 += bflo(pv.y); o3 += bfhi(pv.y);
;           }
;           uint2 w;
;           w.x = pack2(o0, o1); w.y = pack2(o2, o3);
;           *(uint2*)(MP + (size_t)tok * 2048 + cb) = w;
.LBB0_942:
	s_waitcnt lgkmcnt(0)
	s_waitcnt vmcnt(0)
	s_barrier
	v_mbcnt_lo_u32_b32 v128, -1, 0
	v_mbcnt_hi_u32_b32 v128, -1, v128
	s_add_i32 s52, s52, s85
	v_ashrrev_i32_e32 v130, 2, v128
	v_and_b32_e32 v130, -4, v130
	v_add_u32_e32 v134, s52, v130
	s_lshl_b32 s52, s93, 8
	s_or_b32 s52, s52, s86
	v_lshlrev_b32_e32 v128, 2, v128
	v_and_or_b32 v130, v128, 60, s52
	v_ashrrev_i32_e32 v135, 31, v134
	v_ashrrev_i32_e32 v131, 31, v130
	v_lshlrev_b64 v[136:137], 13, v[134:135]
	v_lshlrev_b64 v[130:131], 1, v[130:131]
	v_lshl_add_u64 v[136:137], s[28:29], 0, v[136:137]
	v_lshl_add_u64 v[136:137], v[136:137], 0, v[130:131]
	v_lshl_add_u64 v[132:133], s[4:5], 0, v[130:131]
	v_lshlrev_b64 v[140:141], 12, v[134:135]
	v_add_co_u32_e32 v136, vcc, s91, v136
	v_lshl_add_u64 v[140:141], v[132:133], 0, v[140:141]
	s_nop 0
	v_addc_co_u32_e32 v137, vcc, 0, v137, vcc
	s_mov_b32 s98, s91
	s_mov_b32 s99, 0
	v_add_u32_e32 v242, 0x0, v134
	v_ashrrev_i32_e32 v243, 31, v242
	v_lshlrev_b64 v[244:245], 12, v[242:243]
	v_lshl_add_u64 v[244:245], v[132:133], 0, v[244:245]
	global_load_dwordx2 v[178:179], v[244:245], off
	v_add_u32_e32 v242, 0x0, v134
	v_ashrrev_i32_e32 v243, 31, v242
	v_lshlrev_b64 v[244:245], 13, v[242:243]
	v_lshl_add_u64 v[244:245], s[28:29], 0, v[244:245]
	v_lshl_add_u64 v[244:245], v[244:245], 0, v[130:131]
	v_lshl_add_u64 v[244:245], v[244:245], 0, s[98:99]
	global_load_dwordx2 v[180:181], v[244:245], off
	v_add_u32_e32 v242, 0x1, v134
	v_ashrrev_i32_e32 v243, 31, v242
	v_lshlrev_b64 v[244:245], 12, v[242:243]
	v_lshl_add_u64 v[244:245], v[132:133], 0, v[244:245]
	global_load_dwordx2 v[182:183], v[244:245], off
	v_add_u32_e32 v242, 0x2, v134
	v_ashrrev_i32_e32 v243, 31, v242
	v_lshlrev_b64 v[244:245], 12, v[242:243]
	v_lshl_add_u64 v[244:245], v[132:133], 0, v[244:245]
	global_load_dwordx2 v[184:185], v[244:245], off
	v_add_u32_e32 v242, 0x3, v134
	v_ashrrev_i32_e32 v243, 31, v242
	v_lshlrev_b64 v[244:245], 12, v[242:243]
	v_lshl_add_u64 v[244:245], v[132:133], 0, v[244:245]
	global_load_dwordx2 v[186:187], v[244:245], off
	v_add_u32_e32 v242, 0x1, v134
	v_ashrrev_i32_e32 v243, 31, v242
	v_lshlrev_b64 v[244:245], 13, v[242:243]
	v_lshl_add_u64 v[244:245], s[28:29], 0, v[244:245]
	v_lshl_add_u64 v[244:245], v[244:245], 0, v[130:131]
	v_lshl_add_u64 v[244:245], v[244:245], 0, s[98:99]
	global_load_dwordx2 v[188:189], v[244:245], off
	v_add_u32_e32 v242, 0x2, v134
	v_ashrrev_i32_e32 v243, 31, v242
	v_lshlrev_b64 v[244:245], 13, v[242:243]
	v_lshl_add_u64 v[244:245], s[28:29], 0, v[244:245]
	v_lshl_add_u64 v[244:245], v[244:245], 0, v[130:131]
	v_lshl_add_u64 v[244:245], v[244:245], 0, s[98:99]
	global_load_dwordx2 v[190:191], v[244:245], off
	v_add_u32_e32 v242, 0x3, v134
	v_ashrrev_i32_e32 v243, 31, v242
	v_lshlrev_b64 v[244:245], 13, v[242:243]
	v_lshl_add_u64 v[244:245], s[28:29], 0, v[244:245]
	v_lshl_add_u64 v[244:245], v[244:245], 0, v[130:131]
	v_lshl_add_u64 v[244:245], v[244:245], 0, s[98:99]
	global_load_dwordx2 v[192:193], v[244:245], off
	v_add_u32_e32 v242, 0x10, v134
	v_ashrrev_i32_e32 v243, 31, v242
	v_lshlrev_b64 v[244:245], 13, v[242:243]
	v_lshl_add_u64 v[244:245], s[28:29], 0, v[244:245]
	v_lshl_add_u64 v[244:245], v[244:245], 0, v[130:131]
	v_lshl_add_u64 v[244:245], v[244:245], 0, s[98:99]
	global_load_dwordx2 v[194:195], v[244:245], off
	v_add_u32_e32 v242, 0x10, v134
	v_ashrrev_i32_e32 v243, 31, v242
	v_lshlrev_b64 v[244:245], 12, v[242:243]
	v_lshl_add_u64 v[244:245], v[132:133], 0, v[244:245]
	global_load_dwordx2 v[196:197], v[244:245], off
	v_add_u32_e32 v242, 0x11, v134
	v_ashrrev_i32_e32 v243, 31, v242
	v_lshlrev_b64 v[244:245], 12, v[242:243]
	v_lshl_add_u64 v[244:245], v[132:133], 0, v[244:245]
	global_load_dwordx2 v[198:199], v[244:245], off
	v_add_u32_e32 v242, 0x12, v134
	v_ashrrev_i32_e32 v243, 31, v242
	v_lshlrev_b64 v[244:245], 12, v[242:243]
	v_lshl_add_u64 v[244:245], v[132:133], 0, v[244:245]
	global_load_dwordx2 v[200:201], v[244:245], off
	v_add_u32_e32 v242, 0x13, v134
	v_ashrrev_i32_e32 v243, 31, v242
	v_lshlrev_b64 v[244:245], 12, v[242:243]
	v_lshl_add_u64 v[244:245], v[132:133], 0, v[244:245]
	global_load_dwordx2 v[202:203], v[244:245], off
	v_add_u32_e32 v242, 0x11, v134
	v_ashrrev_i32_e32 v243, 31, v242
	v_lshlrev_b64 v[244:245], 13, v[242:243]
	v_lshl_add_u64 v[244:245], s[28:29], 0, v[244:245]
	v_lshl_add_u64 v[244:245], v[244:245], 0, v[130:131]
	v_lshl_add_u64 v[244:245], v[244:245], 0, s[98:99]
	global_load_dwordx2 v[204:205], v[244:245], off
	v_add_u32_e32 v242, 0x12, v134
	v_ashrrev_i32_e32 v243, 31, v242
	v_lshlrev_b64 v[244:245], 13, v[242:243]
	v_lshl_add_u64 v[244:245], s[28:29], 0, v[244:245]
	v_lshl_add_u64 v[244:245], v[244:245], 0, v[130:131]
	v_lshl_add_u64 v[244:245], v[244:245], 0, s[98:99]
	global_load_dwordx2 v[206:207], v[244:245], off
	v_add_u32_e32 v242, 0x13, v134
	v_ashrrev_i32_e32 v243, 31, v242
	v_lshlrev_b64 v[244:245], 13, v[242:243]
	v_lshl_add_u64 v[244:245], s[28:29], 0, v[244:245]
	v_lshl_add_u64 v[244:245], v[244:245], 0, v[130:131]
	v_lshl_add_u64 v[244:245], v[244:245], 0, s[98:99]
	global_load_dwordx2 v[208:209], v[244:245], off
	v_add_u32_e32 v242, 0x20, v134
	v_ashrrev_i32_e32 v243, 31, v242
	v_lshlrev_b64 v[244:245], 13, v[242:243]
	v_lshl_add_u64 v[244:245], s[28:29], 0, v[244:245]
	v_lshl_add_u64 v[244:245], v[244:245], 0, v[130:131]
	v_lshl_add_u64 v[244:245], v[244:245], 0, s[98:99]
	global_load_dwordx2 v[210:211], v[244:245], off
	v_add_u32_e32 v242, 0x20, v134
	v_ashrrev_i32_e32 v243, 31, v242
	v_lshlrev_b64 v[244:245], 12, v[242:243]
	v_lshl_add_u64 v[244:245], v[132:133], 0, v[244:245]
	global_load_dwordx2 v[212:213], v[244:245], off
	v_add_u32_e32 v242, 0x21, v134
; __device__ __forceinline__ float bflo(unsigned u) { return __uint_as_float(u << 16); }
; __device__ __forceinline__ float bfhi(unsigned u) { return __uint_as_float(u & 0xffff0000u); }
; #define EPI_FENCE(j) do { if ((j) == 0) asm volatile("" ::: "memory"); } while (0)
; template <int PASS>
; __device__ __forceinline__ void gemm3_pass(const Params& p, int wid_s, char* shm) {
;     ...
;         for (int j = 0; j < 4; ++j) { EPI_FENCE(j);
;           int tok = tokbase + ai * 128 + m * 16 + j;
;           uint2 g = *(const uint2*)(G + (size_t)tok * 4096 + (PASS == 0 ? 0 : 2048) + cb);
;           float o0 = bflo(g.x) * acc[ai][0][m][0][j], o1 = bfhi(g.x) * acc[ai][0][m][1][j];
;           float o2 = bflo(g.y) * acc[ai][1][m][0][j], o3 = bfhi(g.y) * acc[ai][1][m][1][j];
;           if (PASS == 1) {
;             uint2 pv = *(const uint2*)(MP + (size_t)tok * 2048 + cb);
;             o0 += bflo(pv.x); o1 += bfhi(pv.x); o2 += bflo(pv.y); o3 += bfhi(pv.y);
;           }
;           uint2 w;
;           w.x = pack2(o0, o1); w.y = pack2(o2, o3);
;           *(uint2*)(MP + (size_t)tok * 2048 + cb) = w;
	v_ashrrev_i32_e32 v243, 31, v242
	v_lshlrev_b64 v[244:245], 12, v[242:243]
	v_lshl_add_u64 v[244:245], v[132:133], 0, v[244:245]
	global_load_dwordx2 v[214:215], v[244:245], off
	v_add_u32_e32 v242, 0x22, v134
	v_ashrrev_i32_e32 v243, 31, v242
	v_lshlrev_b64 v[244:245], 12, v[242:243]
	v_lshl_add_u64 v[244:245], v[132:133], 0, v[244:245]
	global_load_dwordx2 v[216:217], v[244:245], off
	v_add_u32_e32 v242, 0x23, v134
	v_ashrrev_i32_e32 v243, 31, v242
	v_lshlrev_b64 v[244:245], 12, v[242:243]
	v_lshl_add_u64 v[244:245], v[132:133], 0, v[244:245]
	global_load_dwordx2 v[218:219], v[244:245], off
	v_add_u32_e32 v242, 0x21, v134
	v_ashrrev_i32_e32 v243, 31, v242
	v_lshlrev_b64 v[244:245], 13, v[242:243]
	v_lshl_add_u64 v[244:245], s[28:29], 0, v[244:245]
	v_lshl_add_u64 v[244:245], v[244:245], 0, v[130:131]
	v_lshl_add_u64 v[244:245], v[244:245], 0, s[98:99]
	global_load_dwordx2 v[220:221], v[244:245], off
	v_add_u32_e32 v242, 0x22, v134
	v_ashrrev_i32_e32 v243, 31, v242
	v_lshlrev_b64 v[244:245], 13, v[242:243]
	v_lshl_add_u64 v[244:245], s[28:29], 0, v[244:245]
	v_lshl_add_u64 v[244:245], v[244:245], 0, v[130:131]
	v_lshl_add_u64 v[244:245], v[244:245], 0, s[98:99]
	global_load_dwordx2 v[222:223], v[244:245], off
	v_add_u32_e32 v242, 0x23, v134
	v_ashrrev_i32_e32 v243, 31, v242
	v_lshlrev_b64 v[244:245], 13, v[242:243]
	v_lshl_add_u64 v[244:245], s[28:29], 0, v[244:245]
	v_lshl_add_u64 v[244:245], v[244:245], 0, v[130:131]
	v_lshl_add_u64 v[244:245], v[244:245], 0, s[98:99]
	global_load_dwordx2 v[224:225], v[244:245], off
	v_add_u32_e32 v242, 0x30, v134
	v_ashrrev_i32_e32 v243, 31, v242
	v_lshlrev_b64 v[244:245], 13, v[242:243]
	v_lshl_add_u64 v[244:245], s[28:29], 0, v[244:245]
	v_lshl_add_u64 v[244:245], v[244:245], 0, v[130:131]
	v_lshl_add_u64 v[244:245], v[244:245], 0, s[98:99]
	global_load_dwordx2 v[226:227], v[244:245], off
	v_add_u32_e32 v242, 0x30, v134
	v_ashrrev_i32_e32 v243, 31, v242
	v_lshlrev_b64 v[244:245], 12, v[242:243]
	v_lshl_add_u64 v[244:245], v[132:133], 0, v[244:245]
	global_load_dwordx2 v[228:229], v[244:245], off
	v_add_u32_e32 v242, 0x31, v134
	v_ashrrev_i32_e32 v243, 31, v242
	v_lshlrev_b64 v[244:245], 12, v[242:243]
	v_lshl_add_u64 v[244:245], v[132:133], 0, v[244:245]
	global_load_dwordx2 v[230:231], v[244:245], off
	v_add_u32_e32 v242, 0x32, v134
	v_ashrrev_i32_e32 v243, 31, v242
	v_lshlrev_b64 v[244:245], 12, v[242:243]
	v_lshl_add_u64 v[244:245], v[132:133], 0, v[244:245]
	global_load_dwordx2 v[232:233], v[244:245], off
	v_add_u32_e32 v242, 0x33, v134
	v_ashrrev_i32_e32 v243, 31, v242
	v_lshlrev_b64 v[244:245], 12, v[242:243]
	v_lshl_add_u64 v[244:245], v[132:133], 0, v[244:245]
	global_load_dwordx2 v[234:235], v[244:245], off
	v_add_u32_e32 v242, 0x31, v134
	v_ashrrev_i32_e32 v243, 31, v242
	v_lshlrev_b64 v[244:245], 13, v[242:243]
	v_lshl_add_u64 v[244:245], s[28:29], 0, v[244:245]
	v_lshl_add_u64 v[244:245], v[244:245], 0, v[130:131]
	v_lshl_add_u64 v[244:245], v[244:245], 0, s[98:99]
	global_load_dwordx2 v[236:237], v[244:245], off
	v_add_u32_e32 v242, 0x32, v134
	v_ashrrev_i32_e32 v243, 31, v242
	v_lshlrev_b64 v[244:245], 13, v[242:243]
	v_lshl_add_u64 v[244:245], s[28:29], 0, v[244:245]
	v_lshl_add_u64 v[244:245], v[244:245], 0, v[130:131]
	v_lshl_add_u64 v[244:245], v[244:245], 0, s[98:99]
	global_load_dwordx2 v[238:239], v[244:245], off
	v_add_u32_e32 v242, 0x33, v134
	v_ashrrev_i32_e32 v243, 31, v242
	v_lshlrev_b64 v[244:245], 13, v[242:243]
	v_lshl_add_u64 v[244:245], s[28:29], 0, v[244:245]
	v_lshl_add_u64 v[244:245], v[244:245], 0, v[130:131]
	v_lshl_add_u64 v[244:245], v[244:245], 0, s[98:99]
	global_load_dwordx2 v[240:241], v[244:245], off
	s_waitcnt vmcnt(31)
	v_mov_b32_e32 v142, v178
	v_mov_b32_e32 v143, v179
	v_add_u32_e32 v148, 1, v134
	s_waitcnt vmcnt(30)
	v_mov_b32_e32 v136, v180
	v_mov_b32_e32 v137, v181
	v_ashrrev_i32_e32 v149, 31, v148
	v_lshlrev_b64 v[154:155], 13, v[148:149]
	v_mov_b32_e32 v144, v120
	v_mov_b32_e32 v145, v112
	v_mov_b32_e32 v146, v124
	v_mov_b32_e32 v147, v116
	v_add_u32_e32 v150, 2, v134
	v_add_u32_e32 v152, 3, v134
	v_lshl_add_u64 v[154:155], s[28:29], 0, v[154:155]
	v_ashrrev_i32_e32 v151, 31, v150
	v_ashrrev_i32_e32 v153, 31, v152
	v_lshlrev_b64 v[148:149], 12, v[148:149]
	v_lshl_add_u64 v[154:155], v[154:155], 0, v[130:131]
	v_lshlrev_b64 v[156:157], 12, v[150:151]
	v_lshlrev_b64 v[158:159], 12, v[152:153]
	v_lshl_add_u64 v[148:149], v[132:133], 0, v[148:149]
	v_add_co_u32_e32 v154, vcc, s91, v154
	v_lshl_add_u64 v[156:157], v[132:133], 0, v[156:157]
	v_lshl_add_u64 v[158:159], v[132:133], 0, v[158:159]
	s_waitcnt vmcnt(29)
	v_mov_b32_e32 v160, v182
	v_mov_b32_e32 v161, v183
	s_waitcnt vmcnt(28)
	v_mov_b32_e32 v162, v184
	v_mov_b32_e32 v163, v185
	s_waitcnt vmcnt(27)
	v_mov_b32_e32 v164, v186
	v_mov_b32_e32 v165, v187
	v_addc_co_u32_e32 v155, vcc, 0, v155, vcc
	v_mov_b32_e32 v112, v121
	v_lshlrev_b64 v[120:121], 13, v[150:151]
	v_mov_b32_e32 v116, v125
	v_lshl_add_u64 v[120:121], s[28:29], 0, v[120:121]
	v_lshl_add_u64 v[120:121], v[120:121], 0, v[130:131]
	v_add_co_u32_e32 v120, vcc, s91, v120
	v_lshlrev_b32_e32 v166, 16, v142
	v_and_b32_e32 v167, 0xffff0000, v142
	v_lshlrev_b32_e32 v142, 16, v143
	v_and_b32_e32 v143, 0xffff0000, v143
	v_lshlrev_b32_e32 v168, 16, v136
	v_and_b32_e32 v169, 0xffff0000, v136
	v_lshlrev_b32_e32 v136, 16, v137
	v_and_b32_e32 v137, 0xffff0000, v137
	v_pk_fma_f32 v[144:145], v[144:145], v[168:169], v[166:167]
	v_pk_fma_f32 v[136:137], v[146:147], v[136:137], v[142:143]
	v_cvt_pk_bf16_f32 v142, v144, v145
	v_cvt_pk_bf16_f32 v143, v136, v137
	global_store_dwordx2 v[140:141], v[142:143], off
	s_waitcnt vmcnt(27)
; __device__ __forceinline__ float bflo(unsigned u) { return __uint_as_float(u << 16); }
; __device__ __forceinline__ float bfhi(unsigned u) { return __uint_as_float(u & 0xffff0000u); }
; #define EPI_FENCE(j) do { if ((j) == 0) asm volatile("" ::: "memory"); } while (0)
; template <int PASS>
; __device__ __forceinline__ void gemm3_pass(const Params& p, int wid_s, char* shm) {
;     ...
;         for (int j = 0; j < 4; ++j) { EPI_FENCE(j);
;           int tok = tokbase + ai * 128 + m * 16 + j;
;           uint2 g = *(const uint2*)(G + (size_t)tok * 4096 + (PASS == 0 ? 0 : 2048) + cb);
;           float o0 = bflo(g.x) * acc[ai][0][m][0][j], o1 = bfhi(g.x) * acc[ai][0][m][1][j];
;           float o2 = bflo(g.y) * acc[ai][1][m][0][j], o3 = bfhi(g.y) * acc[ai][1][m][1][j];
;           if (PASS == 1) {
;             uint2 pv = *(const uint2*)(MP + (size_t)tok * 2048 + cb);
;             o0 += bflo(pv.x); o1 += bfhi(pv.x); o2 += bflo(pv.y); o3 += bfhi(pv.y);
;           }
;           uint2 w;
;           w.x = pack2(o0, o1); w.y = pack2(o2, o3);
;           *(uint2*)(MP + (size_t)tok * 2048 + cb) = w;
	v_mov_b32_e32 v136, v188
	v_mov_b32_e32 v137, v189
	v_addc_co_u32_e32 v121, vcc, 0, v121, vcc
	v_lshlrev_b32_e32 v124, 16, v160
	v_and_b32_e32 v125, 0xffff0000, v160
	v_lshlrev_b32_e32 v140, 16, v161
	v_and_b32_e32 v141, 0xffff0000, v161
	v_lshlrev_b32_e32 v142, 16, v136
	v_and_b32_e32 v143, 0xffff0000, v136
	v_lshlrev_b32_e32 v136, 16, v137
	v_and_b32_e32 v137, 0xffff0000, v137
	v_pk_fma_f32 v[112:113], v[112:113], v[142:143], v[124:125]
	v_pk_fma_f32 v[116:117], v[116:117], v[136:137], v[140:141]
	v_cvt_pk_bf16_f32 v112, v112, v113
	v_cvt_pk_bf16_f32 v113, v116, v117
	global_store_dwordx2 v[148:149], v[112:113], off
	s_waitcnt vmcnt(27)
	v_mov_b32_e32 v112, v190
	v_mov_b32_e32 v113, v191
	v_lshlrev_b64 v[124:125], 13, v[152:153]
	v_mov_b32_e32 v116, v122
	v_mov_b32_e32 v117, v114
	v_mov_b32_e32 v120, v126
	v_mov_b32_e32 v121, v118
	v_lshl_add_u64 v[124:125], s[28:29], 0, v[124:125]
	v_lshlrev_b32_e32 v136, 16, v162
	v_and_b32_e32 v137, 0xffff0000, v162
	v_lshlrev_b32_e32 v140, 16, v163
	v_and_b32_e32 v141, 0xffff0000, v163
	v_lshl_add_u64 v[124:125], v[124:125], 0, v[130:131]
	v_add_co_u32_e32 v124, vcc, s91, v124
	v_mov_b32_e32 v114, v123
	s_nop 0
	v_addc_co_u32_e32 v125, vcc, 0, v125, vcc
	v_mov_b32_e32 v118, v127
	v_lshlrev_b32_e32 v122, 16, v164
	v_and_b32_e32 v123, 0xffff0000, v164
	v_lshlrev_b32_e32 v142, 16, v112
	v_and_b32_e32 v143, 0xffff0000, v112
	v_lshlrev_b32_e32 v112, 16, v113
	v_and_b32_e32 v113, 0xffff0000, v113
	v_pk_fma_f32 v[116:117], v[116:117], v[142:143], v[136:137]
	v_pk_fma_f32 v[112:113], v[120:121], v[112:113], v[140:141]
	v_cvt_pk_bf16_f32 v116, v116, v117
	v_cvt_pk_bf16_f32 v117, v112, v113
	global_store_dwordx2 v[156:157], v[116:117], off
	s_waitcnt vmcnt(27)
	v_mov_b32_e32 v112, v192
	v_mov_b32_e32 v113, v193
	v_add_u32_e32 v116, 16, v134
	v_ashrrev_i32_e32 v117, 31, v116
	v_lshlrev_b64 v[120:121], 13, v[116:117]
	v_lshlrev_b32_e32 v124, 16, v165
	v_and_b32_e32 v125, 0xffff0000, v165
	v_lshl_add_u64 v[120:121], s[28:29], 0, v[120:121]
	v_lshl_add_u64 v[120:121], v[120:121], 0, v[130:131]
	v_add_co_u32_e32 v120, vcc, s91, v120
	v_lshlrev_b32_e32 v126, 16, v112
	v_and_b32_e32 v127, 0xffff0000, v112
	v_lshlrev_b32_e32 v112, 16, v113
	v_and_b32_e32 v113, 0xffff0000, v113
	v_pk_fma_f32 v[114:115], v[114:115], v[126:127], v[122:123]
	v_pk_fma_f32 v[112:113], v[118:119], v[112:113], v[124:125]
	v_cvt_pk_bf16_f32 v114, v114, v115
	v_cvt_pk_bf16_f32 v115, v112, v113
	global_store_dwordx2 v[158:159], v[114:115], off
	v_lshlrev_b64 v[114:115], 12, v[116:117]
	v_addc_co_u32_e32 v121, vcc, 0, v121, vcc
	v_lshl_add_u64 v[114:115], v[132:133], 0, v[114:115]
	s_waitcnt vmcnt(27)
	v_mov_b32_e32 v112, v194
	v_mov_b32_e32 v113, v195
	s_waitcnt vmcnt(26)
	v_mov_b32_e32 v116, v196
	v_mov_b32_e32 v117, v197
	v_add_u32_e32 v122, 17, v134
	v_ashrrev_i32_e32 v123, 31, v122
	v_lshlrev_b64 v[136:137], 13, v[122:123]
	v_mov_b32_e32 v118, v104
	v_mov_b32_e32 v119, v96
	v_mov_b32_e32 v120, v108
	v_mov_b32_e32 v121, v100
	v_add_u32_e32 v124, 18, v134
	v_add_u32_e32 v126, 19, v134
	v_lshl_add_u64 v[136:137], s[28:29], 0, v[136:137]
	v_ashrrev_i32_e32 v125, 31, v124
	v_ashrrev_i32_e32 v127, 31, v126
	v_lshlrev_b64 v[122:123], 12, v[122:123]
	v_lshl_add_u64 v[136:137], v[136:137], 0, v[130:131]
	v_lshlrev_b64 v[140:141], 12, v[124:125]
	v_lshlrev_b64 v[142:143], 12, v[126:127]
	v_lshl_add_u64 v[122:123], v[132:133], 0, v[122:123]
	v_add_co_u32_e32 v136, vcc, s91, v136
	v_lshl_add_u64 v[140:141], v[132:133], 0, v[140:141]
	v_lshl_add_u64 v[142:143], v[132:133], 0, v[142:143]
	v_addc_co_u32_e32 v137, vcc, 0, v137, vcc
	s_waitcnt vmcnt(25)
	v_mov_b32_e32 v144, v198
	v_mov_b32_e32 v145, v199
	s_waitcnt vmcnt(24)
	v_mov_b32_e32 v146, v200
	v_mov_b32_e32 v147, v201
	s_waitcnt vmcnt(23)
	v_mov_b32_e32 v148, v202
	v_mov_b32_e32 v149, v203
	v_mov_b32_e32 v96, v105
	v_lshlrev_b64 v[104:105], 13, v[124:125]
	v_mov_b32_e32 v100, v109
	v_lshl_add_u64 v[104:105], s[28:29], 0, v[104:105]
	v_lshl_add_u64 v[104:105], v[104:105], 0, v[130:131]
	v_add_co_u32_e32 v104, vcc, s91, v104
	v_lshlrev_b32_e32 v150, 16, v112
	v_and_b32_e32 v151, 0xffff0000, v112
	v_lshlrev_b32_e32 v112, 16, v113
	v_and_b32_e32 v113, 0xffff0000, v113
	v_lshlrev_b32_e32 v152, 16, v116
	v_and_b32_e32 v153, 0xffff0000, v116
	v_lshlrev_b32_e32 v116, 16, v117
	v_and_b32_e32 v117, 0xffff0000, v117
	v_pk_fma_f32 v[118:119], v[118:119], v[150:151], v[152:153]
	v_pk_fma_f32 v[112:113], v[120:121], v[112:113], v[116:117]
	v_cvt_pk_bf16_f32 v116, v118, v119
	v_cvt_pk_bf16_f32 v117, v112, v113
	global_store_dwordx2 v[114:115], v[116:117], off
	s_waitcnt vmcnt(23)
	v_mov_b32_e32 v112, v204
	v_mov_b32_e32 v113, v205
	v_addc_co_u32_e32 v105, vcc, 0, v105, vcc
	v_lshlrev_b32_e32 v108, 16, v144
	v_and_b32_e32 v109, 0xffff0000, v144
	v_lshlrev_b32_e32 v114, 16, v145
	v_and_b32_e32 v115, 0xffff0000, v145
	v_lshlrev_b32_e32 v116, 16, v112
	v_and_b32_e32 v117, 0xffff0000, v112
	v_lshlrev_b32_e32 v112, 16, v113
	v_and_b32_e32 v113, 0xffff0000, v113
	v_pk_fma_f32 v[96:97], v[96:97], v[116:117], v[108:109]
	v_pk_fma_f32 v[100:101], v[100:101], v[112:113], v[114:115]
	v_cvt_pk_bf16_f32 v96, v96, v97
	v_cvt_pk_bf16_f32 v97, v100, v101
	global_store_dwordx2 v[122:123], v[96:97], off
	s_waitcnt vmcnt(23)
; __device__ __forceinline__ float bflo(unsigned u) { return __uint_as_float(u << 16); }
; __device__ __forceinline__ float bfhi(unsigned u) { return __uint_as_float(u & 0xffff0000u); }
; #define EPI_FENCE(j) do { if ((j) == 0) asm volatile("" ::: "memory"); } while (0)
; template <int PASS>
; __device__ __forceinline__ void gemm3_pass(const Params& p, int wid_s, char* shm) {
;     ...
;         for (int j = 0; j < 4; ++j) { EPI_FENCE(j);
;           int tok = tokbase + ai * 128 + m * 16 + j;
;           uint2 g = *(const uint2*)(G + (size_t)tok * 4096 + (PASS == 0 ? 0 : 2048) + cb);
;           float o0 = bflo(g.x) * acc[ai][0][m][0][j], o1 = bfhi(g.x) * acc[ai][0][m][1][j];
;           float o2 = bflo(g.y) * acc[ai][1][m][0][j], o3 = bfhi(g.y) * acc[ai][1][m][1][j];
;           if (PASS == 1) {
;             uint2 pv = *(const uint2*)(MP + (size_t)tok * 2048 + cb);
;             o0 += bflo(pv.x); o1 += bfhi(pv.x); o2 += bflo(pv.y); o3 += bfhi(pv.y);
;           }
;           uint2 w;
;           w.x = pack2(o0, o1); w.y = pack2(o2, o3);
;           *(uint2*)(MP + (size_t)tok * 2048 + cb) = w;
	v_mov_b32_e32 v96, v206
	v_mov_b32_e32 v97, v207
	v_lshlrev_b64 v[108:109], 13, v[126:127]
	v_mov_b32_e32 v100, v106
	v_mov_b32_e32 v101, v98
	v_mov_b32_e32 v104, v110
	v_mov_b32_e32 v105, v102
	v_lshl_add_u64 v[108:109], s[28:29], 0, v[108:109]
	v_lshlrev_b32_e32 v112, 16, v146
	v_and_b32_e32 v113, 0xffff0000, v146
	v_lshlrev_b32_e32 v114, 16, v147
	v_and_b32_e32 v115, 0xffff0000, v147
	v_lshl_add_u64 v[108:109], v[108:109], 0, v[130:131]
	v_add_co_u32_e32 v108, vcc, s91, v108
	v_mov_b32_e32 v98, v107
	s_nop 0
	v_addc_co_u32_e32 v109, vcc, 0, v109, vcc
	v_mov_b32_e32 v102, v111
	v_lshlrev_b32_e32 v106, 16, v148
	v_and_b32_e32 v107, 0xffff0000, v148
	v_lshlrev_b32_e32 v116, 16, v96
	v_and_b32_e32 v117, 0xffff0000, v96
	v_lshlrev_b32_e32 v96, 16, v97
	v_and_b32_e32 v97, 0xffff0000, v97
	v_pk_fma_f32 v[100:101], v[100:101], v[116:117], v[112:113]
	v_pk_fma_f32 v[96:97], v[104:105], v[96:97], v[114:115]
	v_cvt_pk_bf16_f32 v100, v100, v101
	v_cvt_pk_bf16_f32 v101, v96, v97
	global_store_dwordx2 v[140:141], v[100:101], off
	s_waitcnt vmcnt(23)
	v_mov_b32_e32 v96, v208
	v_mov_b32_e32 v97, v209
	v_add_u32_e32 v100, 32, v134
	v_ashrrev_i32_e32 v101, 31, v100
	v_lshlrev_b64 v[104:105], 13, v[100:101]
	v_lshlrev_b32_e32 v108, 16, v149
	v_and_b32_e32 v109, 0xffff0000, v149
	v_lshl_add_u64 v[104:105], s[28:29], 0, v[104:105]
	v_lshl_add_u64 v[104:105], v[104:105], 0, v[130:131]
	v_add_co_u32_e32 v104, vcc, s91, v104
	v_lshlrev_b32_e32 v110, 16, v96
	v_and_b32_e32 v111, 0xffff0000, v96
	v_lshlrev_b32_e32 v96, 16, v97
	v_and_b32_e32 v97, 0xffff0000, v97
	v_pk_fma_f32 v[98:99], v[98:99], v[110:111], v[106:107]
	v_pk_fma_f32 v[96:97], v[102:103], v[96:97], v[108:109]
	v_cvt_pk_bf16_f32 v98, v98, v99
	v_cvt_pk_bf16_f32 v99, v96, v97
	global_store_dwordx2 v[142:143], v[98:99], off
	v_lshlrev_b64 v[98:99], 12, v[100:101]
	v_addc_co_u32_e32 v105, vcc, 0, v105, vcc
	v_lshl_add_u64 v[98:99], v[132:133], 0, v[98:99]
	s_waitcnt vmcnt(23)
	v_mov_b32_e32 v96, v210
	v_mov_b32_e32 v97, v211
	s_waitcnt vmcnt(22)
	v_mov_b32_e32 v100, v212
	v_mov_b32_e32 v101, v213
	v_add_u32_e32 v106, 33, v134
	v_ashrrev_i32_e32 v107, 31, v106
	v_lshlrev_b64 v[112:113], 13, v[106:107]
	v_mov_b32_e32 v102, v88
	v_mov_b32_e32 v103, v80
	v_mov_b32_e32 v104, v92
	v_mov_b32_e32 v105, v84
	v_add_u32_e32 v108, 34, v134
	v_add_u32_e32 v110, 35, v134
	v_lshl_add_u64 v[112:113], s[28:29], 0, v[112:113]
	v_ashrrev_i32_e32 v109, 31, v108
	v_ashrrev_i32_e32 v111, 31, v110
	v_lshlrev_b64 v[106:107], 12, v[106:107]
	v_lshl_add_u64 v[112:113], v[112:113], 0, v[130:131]
	v_lshlrev_b64 v[114:115], 12, v[108:109]
	v_lshlrev_b64 v[116:117], 12, v[110:111]
	v_lshl_add_u64 v[106:107], v[132:133], 0, v[106:107]
	v_add_co_u32_e32 v112, vcc, s91, v112
	v_lshl_add_u64 v[114:115], v[132:133], 0, v[114:115]
	v_lshl_add_u64 v[116:117], v[132:133], 0, v[116:117]
	v_addc_co_u32_e32 v113, vcc, 0, v113, vcc
	s_waitcnt vmcnt(21)
	v_mov_b32_e32 v118, v214
	v_mov_b32_e32 v119, v215
	s_waitcnt vmcnt(20)
	v_mov_b32_e32 v120, v216
	v_mov_b32_e32 v121, v217
	s_waitcnt vmcnt(19)
	v_mov_b32_e32 v122, v218
	v_mov_b32_e32 v123, v219
	v_mov_b32_e32 v80, v89
	v_lshlrev_b64 v[88:89], 13, v[108:109]
	v_mov_b32_e32 v84, v93
	v_lshl_add_u64 v[88:89], s[28:29], 0, v[88:89]
	v_lshl_add_u64 v[88:89], v[88:89], 0, v[130:131]
	v_add_co_u32_e32 v88, vcc, s91, v88
	v_lshlrev_b32_e32 v124, 16, v96
	v_and_b32_e32 v125, 0xffff0000, v96
	v_lshlrev_b32_e32 v96, 16, v97
	v_and_b32_e32 v97, 0xffff0000, v97
	v_lshlrev_b32_e32 v126, 16, v100
	v_and_b32_e32 v127, 0xffff0000, v100
	v_lshlrev_b32_e32 v100, 16, v101
	v_and_b32_e32 v101, 0xffff0000, v101
	v_pk_fma_f32 v[102:103], v[102:103], v[124:125], v[126:127]
	v_pk_fma_f32 v[96:97], v[104:105], v[96:97], v[100:101]
	v_cvt_pk_bf16_f32 v100, v102, v103
	v_cvt_pk_bf16_f32 v101, v96, v97
	global_store_dwordx2 v[98:99], v[100:101], off
	s_waitcnt vmcnt(19)
	v_mov_b32_e32 v96, v220
	v_mov_b32_e32 v97, v221
	v_addc_co_u32_e32 v89, vcc, 0, v89, vcc
	v_lshlrev_b32_e32 v92, 16, v118
	v_and_b32_e32 v93, 0xffff0000, v118
	v_lshlrev_b32_e32 v98, 16, v119
	v_and_b32_e32 v99, 0xffff0000, v119
	v_lshlrev_b32_e32 v100, 16, v96
	v_and_b32_e32 v101, 0xffff0000, v96
	v_lshlrev_b32_e32 v96, 16, v97
	v_and_b32_e32 v97, 0xffff0000, v97
	v_pk_fma_f32 v[80:81], v[80:81], v[100:101], v[92:93]
	v_pk_fma_f32 v[84:85], v[84:85], v[96:97], v[98:99]
	v_cvt_pk_bf16_f32 v80, v80, v81
	v_cvt_pk_bf16_f32 v81, v84, v85
	global_store_dwordx2 v[106:107], v[80:81], off
	s_waitcnt vmcnt(19)
	v_mov_b32_e32 v80, v222
	v_mov_b32_e32 v81, v223
	v_lshlrev_b64 v[92:93], 13, v[110:111]
	v_mov_b32_e32 v84, v90
	v_mov_b32_e32 v85, v82
	v_mov_b32_e32 v88, v94
	v_mov_b32_e32 v89, v86
	v_lshl_add_u64 v[92:93], s[28:29], 0, v[92:93]
	v_lshlrev_b32_e32 v96, 16, v120
	v_and_b32_e32 v97, 0xffff0000, v120
	v_lshlrev_b32_e32 v98, 16, v121
	v_and_b32_e32 v99, 0xffff0000, v121
	v_lshl_add_u64 v[92:93], v[92:93], 0, v[130:131]
	v_add_co_u32_e32 v92, vcc, s91, v92
	v_mov_b32_e32 v82, v91
	s_nop 0
	v_addc_co_u32_e32 v93, vcc, 0, v93, vcc
	v_mov_b32_e32 v86, v95
	v_lshlrev_b32_e32 v90, 16, v122
	v_and_b32_e32 v91, 0xffff0000, v122
	v_lshlrev_b32_e32 v100, 16, v80
	v_and_b32_e32 v101, 0xffff0000, v80
	v_lshlrev_b32_e32 v80, 16, v81
	v_and_b32_e32 v81, 0xffff0000, v81
	v_pk_fma_f32 v[84:85], v[84:85], v[100:101], v[96:97]
	v_pk_fma_f32 v[80:81], v[88:89], v[80:81], v[98:99]
	v_cvt_pk_bf16_f32 v84, v84, v85
	v_cvt_pk_bf16_f32 v85, v80, v81
	global_store_dwordx2 v[114:115], v[84:85], off
	s_waitcnt vmcnt(19)
; __device__ __forceinline__ float bflo(unsigned u) { return __uint_as_float(u << 16); }
; __device__ __forceinline__ float bfhi(unsigned u) { return __uint_as_float(u & 0xffff0000u); }
; #define EPI_FENCE(j) do { if ((j) == 0) asm volatile("" ::: "memory"); } while (0)
; template <int PASS>
; __device__ __forceinline__ void gemm3_pass(const Params& p, int wid_s, char* shm) {
;     ...
;         for (int j = 0; j < 4; ++j) { EPI_FENCE(j);
;           int tok = tokbase + ai * 128 + m * 16 + j;
;           uint2 g = *(const uint2*)(G + (size_t)tok * 4096 + (PASS == 0 ? 0 : 2048) + cb);
;           float o0 = bflo(g.x) * acc[ai][0][m][0][j], o1 = bfhi(g.x) * acc[ai][0][m][1][j];
;           float o2 = bflo(g.y) * acc[ai][1][m][0][j], o3 = bfhi(g.y) * acc[ai][1][m][1][j];
;           if (PASS == 1) {
;             uint2 pv = *(const uint2*)(MP + (size_t)tok * 2048 + cb);
;             o0 += bflo(pv.x); o1 += bfhi(pv.x); o2 += bflo(pv.y); o3 += bfhi(pv.y);
;           }
;           uint2 w;
;           w.x = pack2(o0, o1); w.y = pack2(o2, o3);
;           *(uint2*)(MP + (size_t)tok * 2048 + cb) = w;
	v_mov_b32_e32 v80, v224
	v_mov_b32_e32 v81, v225
	v_add_u32_e32 v84, 48, v134
	v_ashrrev_i32_e32 v85, 31, v84
	v_lshlrev_b64 v[88:89], 13, v[84:85]
	v_lshlrev_b32_e32 v92, 16, v123
	v_and_b32_e32 v93, 0xffff0000, v123
	v_lshl_add_u64 v[88:89], s[28:29], 0, v[88:89]
	v_lshl_add_u64 v[88:89], v[88:89], 0, v[130:131]
	v_add_co_u32_e32 v88, vcc, s91, v88
	v_lshlrev_b32_e32 v94, 16, v80
	v_and_b32_e32 v95, 0xffff0000, v80
	v_lshlrev_b32_e32 v80, 16, v81
	v_and_b32_e32 v81, 0xffff0000, v81
	v_pk_fma_f32 v[82:83], v[82:83], v[94:95], v[90:91]
	v_pk_fma_f32 v[80:81], v[86:87], v[80:81], v[92:93]
	v_cvt_pk_bf16_f32 v82, v82, v83
	v_cvt_pk_bf16_f32 v83, v80, v81
	global_store_dwordx2 v[116:117], v[82:83], off
	v_lshlrev_b64 v[82:83], 12, v[84:85]
	v_addc_co_u32_e32 v89, vcc, 0, v89, vcc
	v_lshl_add_u64 v[82:83], v[132:133], 0, v[82:83]
	s_waitcnt vmcnt(19)
	v_mov_b32_e32 v80, v226
	v_mov_b32_e32 v81, v227
	s_waitcnt vmcnt(18)
	v_mov_b32_e32 v84, v228
	v_mov_b32_e32 v85, v229
	v_add_u32_e32 v90, 49, v134
	v_ashrrev_i32_e32 v91, 31, v90
	v_lshlrev_b64 v[96:97], 13, v[90:91]
	v_mov_b32_e32 v86, v72
	v_mov_b32_e32 v87, v64
	v_mov_b32_e32 v88, v76
	v_mov_b32_e32 v89, v68
	v_add_u32_e32 v92, 50, v134
	v_add_u32_e32 v94, 51, v134
	v_lshl_add_u64 v[96:97], s[28:29], 0, v[96:97]
	v_ashrrev_i32_e32 v93, 31, v92
	v_ashrrev_i32_e32 v95, 31, v94
	v_lshlrev_b64 v[90:91], 12, v[90:91]
	v_lshl_add_u64 v[96:97], v[96:97], 0, v[130:131]
	v_lshlrev_b64 v[98:99], 12, v[92:93]
	v_lshlrev_b64 v[100:101], 12, v[94:95]
	v_lshl_add_u64 v[90:91], v[132:133], 0, v[90:91]
	v_add_co_u32_e32 v96, vcc, s91, v96
	v_lshl_add_u64 v[98:99], v[132:133], 0, v[98:99]
	v_lshl_add_u64 v[100:101], v[132:133], 0, v[100:101]
	v_addc_co_u32_e32 v97, vcc, 0, v97, vcc
	s_waitcnt vmcnt(17)
	v_mov_b32_e32 v102, v230
	v_mov_b32_e32 v103, v231
	s_waitcnt vmcnt(16)
	v_mov_b32_e32 v104, v232
	v_mov_b32_e32 v105, v233
	s_waitcnt vmcnt(15)
	v_mov_b32_e32 v106, v234
	v_mov_b32_e32 v107, v235
	v_mov_b32_e32 v64, v73
	v_lshlrev_b64 v[72:73], 13, v[92:93]
	v_mov_b32_e32 v68, v77
	v_lshl_add_u64 v[72:73], s[28:29], 0, v[72:73]
	v_lshl_add_u64 v[72:73], v[72:73], 0, v[130:131]
	v_add_co_u32_e32 v72, vcc, s91, v72
	v_lshlrev_b32_e32 v108, 16, v80
	v_and_b32_e32 v109, 0xffff0000, v80
	v_lshlrev_b32_e32 v80, 16, v81
	v_and_b32_e32 v81, 0xffff0000, v81
	v_lshlrev_b32_e32 v110, 16, v84
	v_and_b32_e32 v111, 0xffff0000, v84
	v_lshlrev_b32_e32 v84, 16, v85
	v_and_b32_e32 v85, 0xffff0000, v85
	v_pk_fma_f32 v[86:87], v[86:87], v[108:109], v[110:111]
	v_pk_fma_f32 v[80:81], v[88:89], v[80:81], v[84:85]
	v_cvt_pk_bf16_f32 v84, v86, v87
	v_cvt_pk_bf16_f32 v85, v80, v81
	global_store_dwordx2 v[82:83], v[84:85], off
	s_waitcnt vmcnt(15)
	v_mov_b32_e32 v80, v236
	v_mov_b32_e32 v81, v237
	v_addc_co_u32_e32 v73, vcc, 0, v73, vcc
	v_lshlrev_b32_e32 v76, 16, v102
	v_and_b32_e32 v77, 0xffff0000, v102
	v_lshlrev_b32_e32 v82, 16, v103
	v_and_b32_e32 v83, 0xffff0000, v103
	v_lshlrev_b32_e32 v84, 16, v80
	v_and_b32_e32 v85, 0xffff0000, v80
	v_lshlrev_b32_e32 v80, 16, v81
	v_and_b32_e32 v81, 0xffff0000, v81
	v_pk_fma_f32 v[64:65], v[64:65], v[84:85], v[76:77]
	v_pk_fma_f32 v[68:69], v[68:69], v[80:81], v[82:83]
	v_cvt_pk_bf16_f32 v64, v64, v65
	v_cvt_pk_bf16_f32 v65, v68, v69
	global_store_dwordx2 v[90:91], v[64:65], off
	s_waitcnt vmcnt(15)
	v_mov_b32_e32 v64, v238
	v_mov_b32_e32 v65, v239
	v_lshlrev_b64 v[76:77], 13, v[94:95]
	v_mov_b32_e32 v68, v74
	v_mov_b32_e32 v69, v66
	v_mov_b32_e32 v72, v78
	v_mov_b32_e32 v73, v70
	v_lshl_add_u64 v[76:77], s[28:29], 0, v[76:77]
	v_lshlrev_b32_e32 v80, 16, v104
	v_and_b32_e32 v81, 0xffff0000, v104
	v_lshlrev_b32_e32 v82, 16, v105
	v_and_b32_e32 v83, 0xffff0000, v105
	v_lshl_add_u64 v[76:77], v[76:77], 0, v[130:131]
	v_add_co_u32_e32 v76, vcc, s91, v76
	v_mov_b32_e32 v66, v75
	s_nop 0
	v_addc_co_u32_e32 v77, vcc, 0, v77, vcc
	v_mov_b32_e32 v70, v79
	v_lshlrev_b32_e32 v74, 16, v106
	v_and_b32_e32 v75, 0xffff0000, v106
	v_lshlrev_b32_e32 v84, 16, v64
	v_and_b32_e32 v85, 0xffff0000, v64
	v_lshlrev_b32_e32 v64, 16, v65
	v_and_b32_e32 v65, 0xffff0000, v65
	v_pk_fma_f32 v[68:69], v[68:69], v[84:85], v[80:81]
	v_pk_fma_f32 v[64:65], v[72:73], v[64:65], v[82:83]
	v_cvt_pk_bf16_f32 v68, v68, v69
	v_cvt_pk_bf16_f32 v69, v64, v65
	global_store_dwordx2 v[98:99], v[68:69], off
	s_waitcnt vmcnt(15)
; __device__ __forceinline__ float bflo(unsigned u) { return __uint_as_float(u << 16); }
; __device__ __forceinline__ float bfhi(unsigned u) { return __uint_as_float(u & 0xffff0000u); }
; #define EPI_FENCE(j) do { if ((j) == 0) asm volatile("" ::: "memory"); } while (0)
; template <int PASS>
; __device__ __forceinline__ void gemm3_pass(const Params& p, int wid_s, char* shm) {
;     ...
;         for (int j = 0; j < 4; ++j) { EPI_FENCE(j);
;           int tok = tokbase + ai * 128 + m * 16 + j;
;           uint2 g = *(const uint2*)(G + (size_t)tok * 4096 + (PASS == 0 ? 0 : 2048) + cb);
;           float o0 = bflo(g.x) * acc[ai][0][m][0][j], o1 = bfhi(g.x) * acc[ai][0][m][1][j];
;           float o2 = bflo(g.y) * acc[ai][1][m][0][j], o3 = bfhi(g.y) * acc[ai][1][m][1][j];
;           if (PASS == 1) {
;             uint2 pv = *(const uint2*)(MP + (size_t)tok * 2048 + cb);
;             o0 += bflo(pv.x); o1 += bfhi(pv.x); o2 += bflo(pv.y); o3 += bfhi(pv.y);
;           }
;           uint2 w;
;           w.x = pack2(o0, o1); w.y = pack2(o2, o3);
;           *(uint2*)(MP + (size_t)tok * 2048 + cb) = w;
	v_mov_b32_e32 v64, v240
	v_mov_b32_e32 v65, v241
	v_add_u32_e32 v242, 0x80, v134
	v_ashrrev_i32_e32 v243, 31, v242
	v_lshlrev_b64 v[244:245], 13, v[242:243]
	v_lshl_add_u64 v[244:245], s[28:29], 0, v[244:245]
	v_lshl_add_u64 v[244:245], v[244:245], 0, v[130:131]
	v_lshl_add_u64 v[244:245], v[244:245], 0, s[98:99]
	global_load_dwordx2 v[178:179], v[244:245], off
	v_add_u32_e32 v242, 0x80, v134
	v_ashrrev_i32_e32 v243, 31, v242
	v_lshlrev_b64 v[244:245], 12, v[242:243]
	v_lshl_add_u64 v[244:245], v[132:133], 0, v[244:245]
	global_load_dwordx2 v[180:181], v[244:245], off
	v_add_u32_e32 v242, 0x81, v134
	v_ashrrev_i32_e32 v243, 31, v242
	v_lshlrev_b64 v[244:245], 12, v[242:243]
	v_lshl_add_u64 v[244:245], v[132:133], 0, v[244:245]
	global_load_dwordx2 v[182:183], v[244:245], off
	v_add_u32_e32 v242, 0x82, v134
	v_ashrrev_i32_e32 v243, 31, v242
	v_lshlrev_b64 v[244:245], 12, v[242:243]
	v_lshl_add_u64 v[244:245], v[132:133], 0, v[244:245]
	global_load_dwordx2 v[184:185], v[244:245], off
	v_add_u32_e32 v242, 0x83, v134
	v_ashrrev_i32_e32 v243, 31, v242
	v_lshlrev_b64 v[244:245], 12, v[242:243]
	v_lshl_add_u64 v[244:245], v[132:133], 0, v[244:245]
	global_load_dwordx2 v[186:187], v[244:245], off
	v_add_u32_e32 v242, 0x81, v134
	v_ashrrev_i32_e32 v243, 31, v242
	v_lshlrev_b64 v[244:245], 13, v[242:243]
	v_lshl_add_u64 v[244:245], s[28:29], 0, v[244:245]
	v_lshl_add_u64 v[244:245], v[244:245], 0, v[130:131]
	v_lshl_add_u64 v[244:245], v[244:245], 0, s[98:99]
	global_load_dwordx2 v[188:189], v[244:245], off
	v_add_u32_e32 v242, 0x82, v134
	v_ashrrev_i32_e32 v243, 31, v242
	v_lshlrev_b64 v[244:245], 13, v[242:243]
	v_lshl_add_u64 v[244:245], s[28:29], 0, v[244:245]
	v_lshl_add_u64 v[244:245], v[244:245], 0, v[130:131]
	v_lshl_add_u64 v[244:245], v[244:245], 0, s[98:99]
	global_load_dwordx2 v[190:191], v[244:245], off
	v_add_u32_e32 v242, 0x83, v134
	v_ashrrev_i32_e32 v243, 31, v242
	v_lshlrev_b64 v[244:245], 13, v[242:243]
	v_lshl_add_u64 v[244:245], s[28:29], 0, v[244:245]
	v_lshl_add_u64 v[244:245], v[244:245], 0, v[130:131]
	v_lshl_add_u64 v[244:245], v[244:245], 0, s[98:99]
	global_load_dwordx2 v[192:193], v[244:245], off
	v_add_u32_e32 v242, 0x90, v134
	v_ashrrev_i32_e32 v243, 31, v242
	v_lshlrev_b64 v[244:245], 13, v[242:243]
	v_lshl_add_u64 v[244:245], s[28:29], 0, v[244:245]
	v_lshl_add_u64 v[244:245], v[244:245], 0, v[130:131]
	v_lshl_add_u64 v[244:245], v[244:245], 0, s[98:99]
	global_load_dwordx2 v[194:195], v[244:245], off
	v_add_u32_e32 v242, 0x90, v134
	v_ashrrev_i32_e32 v243, 31, v242
	v_lshlrev_b64 v[244:245], 12, v[242:243]
	v_lshl_add_u64 v[244:245], v[132:133], 0, v[244:245]
	global_load_dwordx2 v[196:197], v[244:245], off
	v_add_u32_e32 v242, 0x91, v134
	v_ashrrev_i32_e32 v243, 31, v242
	v_lshlrev_b64 v[244:245], 12, v[242:243]
	v_lshl_add_u64 v[244:245], v[132:133], 0, v[244:245]
	global_load_dwordx2 v[198:199], v[244:245], off
	v_add_u32_e32 v242, 0x92, v134
	v_ashrrev_i32_e32 v243, 31, v242
	v_lshlrev_b64 v[244:245], 12, v[242:243]
	v_lshl_add_u64 v[244:245], v[132:133], 0, v[244:245]
	global_load_dwordx2 v[200:201], v[244:245], off
	v_add_u32_e32 v242, 0x93, v134
	v_ashrrev_i32_e32 v243, 31, v242
	v_lshlrev_b64 v[244:245], 12, v[242:243]
	v_lshl_add_u64 v[244:245], v[132:133], 0, v[244:245]
	global_load_dwordx2 v[202:203], v[244:245], off
	v_add_u32_e32 v242, 0x91, v134
	v_ashrrev_i32_e32 v243, 31, v242
	v_lshlrev_b64 v[244:245], 13, v[242:243]
	v_lshl_add_u64 v[244:245], s[28:29], 0, v[244:245]
	v_lshl_add_u64 v[244:245], v[244:245], 0, v[130:131]
	v_lshl_add_u64 v[244:245], v[244:245], 0, s[98:99]
	global_load_dwordx2 v[204:205], v[244:245], off
	v_add_u32_e32 v242, 0x92, v134
	v_ashrrev_i32_e32 v243, 31, v242
	v_lshlrev_b64 v[244:245], 13, v[242:243]
	v_lshl_add_u64 v[244:245], s[28:29], 0, v[244:245]
	v_lshl_add_u64 v[244:245], v[244:245], 0, v[130:131]
	v_lshl_add_u64 v[244:245], v[244:245], 0, s[98:99]
	global_load_dwordx2 v[206:207], v[244:245], off
	v_add_u32_e32 v242, 0x93, v134
	v_ashrrev_i32_e32 v243, 31, v242
	v_lshlrev_b64 v[244:245], 13, v[242:243]
	v_lshl_add_u64 v[244:245], s[28:29], 0, v[244:245]
	v_lshl_add_u64 v[244:245], v[244:245], 0, v[130:131]
	v_lshl_add_u64 v[244:245], v[244:245], 0, s[98:99]
	global_load_dwordx2 v[208:209], v[244:245], off
	v_add_u32_e32 v242, 0xa0, v134
	v_ashrrev_i32_e32 v243, 31, v242
	v_lshlrev_b64 v[244:245], 13, v[242:243]
	v_lshl_add_u64 v[244:245], s[28:29], 0, v[244:245]
	v_lshl_add_u64 v[244:245], v[244:245], 0, v[130:131]
	v_lshl_add_u64 v[244:245], v[244:245], 0, s[98:99]
	global_load_dwordx2 v[210:211], v[244:245], off
	v_add_u32_e32 v242, 0xa0, v134
	v_ashrrev_i32_e32 v243, 31, v242
	v_lshlrev_b64 v[244:245], 12, v[242:243]
	v_lshl_add_u64 v[244:245], v[132:133], 0, v[244:245]
	global_load_dwordx2 v[212:213], v[244:245], off
	v_add_u32_e32 v242, 0xa1, v134
	v_ashrrev_i32_e32 v243, 31, v242
	v_lshlrev_b64 v[244:245], 12, v[242:243]
	v_lshl_add_u64 v[244:245], v[132:133], 0, v[244:245]
	global_load_dwordx2 v[214:215], v[244:245], off
	v_add_u32_e32 v242, 0xa2, v134
	v_ashrrev_i32_e32 v243, 31, v242
	v_lshlrev_b64 v[244:245], 12, v[242:243]
	v_lshl_add_u64 v[244:245], v[132:133], 0, v[244:245]
	global_load_dwordx2 v[216:217], v[244:245], off
	v_add_u32_e32 v242, 0xa3, v134
	v_ashrrev_i32_e32 v243, 31, v242
	v_lshlrev_b64 v[244:245], 12, v[242:243]
	v_lshl_add_u64 v[244:245], v[132:133], 0, v[244:245]
	global_load_dwordx2 v[218:219], v[244:245], off
	v_add_u32_e32 v242, 0xa1, v134
	v_ashrrev_i32_e32 v243, 31, v242
	v_lshlrev_b64 v[244:245], 13, v[242:243]
	v_lshl_add_u64 v[244:245], s[28:29], 0, v[244:245]
	v_lshl_add_u64 v[244:245], v[244:245], 0, v[130:131]
; __device__ __forceinline__ float bflo(unsigned u) { return __uint_as_float(u << 16); }
; __device__ __forceinline__ float bfhi(unsigned u) { return __uint_as_float(u & 0xffff0000u); }
; #define EPI_FENCE(j) do { if ((j) == 0) asm volatile("" ::: "memory"); } while (0)
; template <int PASS>
; __device__ __forceinline__ void gemm3_pass(const Params& p, int wid_s, char* shm) {
;     ...
;         for (int j = 0; j < 4; ++j) { EPI_FENCE(j);
;           int tok = tokbase + ai * 128 + m * 16 + j;
;           uint2 g = *(const uint2*)(G + (size_t)tok * 4096 + (PASS == 0 ? 0 : 2048) + cb);
;           float o0 = bflo(g.x) * acc[ai][0][m][0][j], o1 = bfhi(g.x) * acc[ai][0][m][1][j];
;           float o2 = bflo(g.y) * acc[ai][1][m][0][j], o3 = bfhi(g.y) * acc[ai][1][m][1][j];
;           if (PASS == 1) {
;             uint2 pv = *(const uint2*)(MP + (size_t)tok * 2048 + cb);
;             o0 += bflo(pv.x); o1 += bfhi(pv.x); o2 += bflo(pv.y); o3 += bfhi(pv.y);
;           }
;           uint2 w;
;           w.x = pack2(o0, o1); w.y = pack2(o2, o3);
;           *(uint2*)(MP + (size_t)tok * 2048 + cb) = w;
	v_lshl_add_u64 v[244:245], v[244:245], 0, s[98:99]
	global_load_dwordx2 v[220:221], v[244:245], off
	v_add_u32_e32 v242, 0xa2, v134
	v_ashrrev_i32_e32 v243, 31, v242
	v_lshlrev_b64 v[244:245], 13, v[242:243]
	v_lshl_add_u64 v[244:245], s[28:29], 0, v[244:245]
	v_lshl_add_u64 v[244:245], v[244:245], 0, v[130:131]
	v_lshl_add_u64 v[244:245], v[244:245], 0, s[98:99]
	global_load_dwordx2 v[222:223], v[244:245], off
	v_add_u32_e32 v242, 0xa3, v134
	v_ashrrev_i32_e32 v243, 31, v242
	v_lshlrev_b64 v[244:245], 13, v[242:243]
	v_lshl_add_u64 v[244:245], s[28:29], 0, v[244:245]
	v_lshl_add_u64 v[244:245], v[244:245], 0, v[130:131]
	v_lshl_add_u64 v[244:245], v[244:245], 0, s[98:99]
	global_load_dwordx2 v[224:225], v[244:245], off
	v_add_u32_e32 v242, 0xb0, v134
	v_ashrrev_i32_e32 v243, 31, v242
	v_lshlrev_b64 v[244:245], 13, v[242:243]
	v_lshl_add_u64 v[244:245], s[28:29], 0, v[244:245]
	v_lshl_add_u64 v[244:245], v[244:245], 0, v[130:131]
	v_lshl_add_u64 v[244:245], v[244:245], 0, s[98:99]
	global_load_dwordx2 v[226:227], v[244:245], off
	v_add_u32_e32 v242, 0xb0, v134
	v_ashrrev_i32_e32 v243, 31, v242
	v_lshlrev_b64 v[244:245], 12, v[242:243]
	v_lshl_add_u64 v[244:245], v[132:133], 0, v[244:245]
	global_load_dwordx2 v[228:229], v[244:245], off
	v_add_u32_e32 v242, 0xb1, v134
	v_ashrrev_i32_e32 v243, 31, v242
	v_lshlrev_b64 v[244:245], 12, v[242:243]
	v_lshl_add_u64 v[244:245], v[132:133], 0, v[244:245]
	global_load_dwordx2 v[230:231], v[244:245], off
	v_add_u32_e32 v242, 0xb2, v134
	v_ashrrev_i32_e32 v243, 31, v242
	v_lshlrev_b64 v[244:245], 12, v[242:243]
	v_lshl_add_u64 v[244:245], v[132:133], 0, v[244:245]
	global_load_dwordx2 v[232:233], v[244:245], off
	v_add_u32_e32 v242, 0xb3, v134
	v_ashrrev_i32_e32 v243, 31, v242
	v_lshlrev_b64 v[244:245], 12, v[242:243]
	v_lshl_add_u64 v[244:245], v[132:133], 0, v[244:245]
	global_load_dwordx2 v[234:235], v[244:245], off
	v_add_u32_e32 v242, 0xb1, v134
	v_ashrrev_i32_e32 v243, 31, v242
	v_lshlrev_b64 v[244:245], 13, v[242:243]
	v_lshl_add_u64 v[244:245], s[28:29], 0, v[244:245]
	v_lshl_add_u64 v[244:245], v[244:245], 0, v[130:131]
	v_lshl_add_u64 v[244:245], v[244:245], 0, s[98:99]
	global_load_dwordx2 v[236:237], v[244:245], off
	v_add_u32_e32 v242, 0xb2, v134
	v_ashrrev_i32_e32 v243, 31, v242
	v_lshlrev_b64 v[244:245], 13, v[242:243]
	v_lshl_add_u64 v[244:245], s[28:29], 0, v[244:245]
	v_lshl_add_u64 v[244:245], v[244:245], 0, v[130:131]
	v_lshl_add_u64 v[244:245], v[244:245], 0, s[98:99]
	global_load_dwordx2 v[238:239], v[244:245], off
	v_add_u32_e32 v242, 0xb3, v134
	v_ashrrev_i32_e32 v243, 31, v242
	v_lshlrev_b64 v[244:245], 13, v[242:243]
	v_lshl_add_u64 v[244:245], s[28:29], 0, v[244:245]
	v_lshl_add_u64 v[244:245], v[244:245], 0, v[130:131]
	v_lshl_add_u64 v[244:245], v[244:245], 0, s[98:99]
	global_load_dwordx2 v[240:241], v[244:245], off
	v_add_u32_e32 v68, 0x80, v134
	v_ashrrev_i32_e32 v69, 31, v68
	v_lshlrev_b64 v[72:73], 13, v[68:69]
	v_lshlrev_b32_e32 v76, 16, v107
	v_and_b32_e32 v77, 0xffff0000, v107
	v_lshl_add_u64 v[72:73], s[28:29], 0, v[72:73]
	v_lshl_add_u64 v[72:73], v[72:73], 0, v[130:131]
	v_add_co_u32_e32 v72, vcc, s91, v72
	v_lshlrev_b32_e32 v78, 16, v64
	v_and_b32_e32 v79, 0xffff0000, v64
	v_lshlrev_b32_e32 v64, 16, v65
	v_and_b32_e32 v65, 0xffff0000, v65
	v_pk_fma_f32 v[66:67], v[66:67], v[78:79], v[74:75]
	v_pk_fma_f32 v[64:65], v[70:71], v[64:65], v[76:77]
	v_cvt_pk_bf16_f32 v66, v66, v67
	v_cvt_pk_bf16_f32 v67, v64, v65
	global_store_dwordx2 v[100:101], v[66:67], off
	v_lshlrev_b64 v[66:67], 12, v[68:69]
	v_addc_co_u32_e32 v73, vcc, 0, v73, vcc
	v_lshl_add_u64 v[66:67], v[132:133], 0, v[66:67]
	s_waitcnt vmcnt(32)
	v_mov_b32_e32 v64, v178
	v_mov_b32_e32 v65, v179
	s_waitcnt vmcnt(31)
	v_mov_b32_e32 v68, v180
	v_mov_b32_e32 v69, v181
	v_add_u32_e32 v74, 0x81, v134
	v_ashrrev_i32_e32 v75, 31, v74
	v_lshlrev_b64 v[80:81], 13, v[74:75]
	v_mov_b32_e32 v70, v56
	v_mov_b32_e32 v71, v48
	v_mov_b32_e32 v72, v60
	v_mov_b32_e32 v73, v52
	v_add_u32_e32 v76, 0x82, v134
	v_add_u32_e32 v78, 0x83, v134
	v_lshl_add_u64 v[80:81], s[28:29], 0, v[80:81]
	v_ashrrev_i32_e32 v77, 31, v76
	v_ashrrev_i32_e32 v79, 31, v78
	v_lshlrev_b64 v[74:75], 12, v[74:75]
	v_lshl_add_u64 v[80:81], v[80:81], 0, v[130:131]
	v_lshlrev_b64 v[82:83], 12, v[76:77]
	v_lshlrev_b64 v[84:85], 12, v[78:79]
	v_lshl_add_u64 v[74:75], v[132:133], 0, v[74:75]
	v_add_co_u32_e32 v80, vcc, s91, v80
	v_lshl_add_u64 v[82:83], v[132:133], 0, v[82:83]
	v_lshl_add_u64 v[84:85], v[132:133], 0, v[84:85]
	v_addc_co_u32_e32 v81, vcc, 0, v81, vcc
	s_waitcnt vmcnt(30)
	v_mov_b32_e32 v86, v182
	v_mov_b32_e32 v87, v183
	s_waitcnt vmcnt(29)
	v_mov_b32_e32 v88, v184
	v_mov_b32_e32 v89, v185
	s_waitcnt vmcnt(28)
	v_mov_b32_e32 v90, v186
	v_mov_b32_e32 v91, v187
	v_mov_b32_e32 v48, v57
	v_lshlrev_b64 v[56:57], 13, v[76:77]
	v_mov_b32_e32 v52, v61
	v_lshl_add_u64 v[56:57], s[28:29], 0, v[56:57]
	v_lshl_add_u64 v[56:57], v[56:57], 0, v[130:131]
	v_add_co_u32_e32 v56, vcc, s91, v56
	v_lshlrev_b32_e32 v92, 16, v64
	v_and_b32_e32 v93, 0xffff0000, v64
	v_lshlrev_b32_e32 v64, 16, v65
	v_and_b32_e32 v65, 0xffff0000, v65
	v_lshlrev_b32_e32 v94, 16, v68
	v_and_b32_e32 v95, 0xffff0000, v68
	v_lshlrev_b32_e32 v68, 16, v69
	v_and_b32_e32 v69, 0xffff0000, v69
	v_pk_fma_f32 v[70:71], v[70:71], v[92:93], v[94:95]
	v_pk_fma_f32 v[64:65], v[72:73], v[64:65], v[68:69]
	v_cvt_pk_bf16_f32 v68, v70, v71
	v_cvt_pk_bf16_f32 v69, v64, v65
	global_store_dwordx2 v[66:67], v[68:69], off
	s_waitcnt vmcnt(28)
; __device__ __forceinline__ float bflo(unsigned u) { return __uint_as_float(u << 16); }
; __device__ __forceinline__ float bfhi(unsigned u) { return __uint_as_float(u & 0xffff0000u); }
; #define EPI_FENCE(j) do { if ((j) == 0) asm volatile("" ::: "memory"); } while (0)
; template <int PASS>
; __device__ __forceinline__ void gemm3_pass(const Params& p, int wid_s, char* shm) {
;     ...
;         for (int j = 0; j < 4; ++j) { EPI_FENCE(j);
;           int tok = tokbase + ai * 128 + m * 16 + j;
;           uint2 g = *(const uint2*)(G + (size_t)tok * 4096 + (PASS == 0 ? 0 : 2048) + cb);
;           float o0 = bflo(g.x) * acc[ai][0][m][0][j], o1 = bfhi(g.x) * acc[ai][0][m][1][j];
;           float o2 = bflo(g.y) * acc[ai][1][m][0][j], o3 = bfhi(g.y) * acc[ai][1][m][1][j];
;           if (PASS == 1) {
;             uint2 pv = *(const uint2*)(MP + (size_t)tok * 2048 + cb);
;             o0 += bflo(pv.x); o1 += bfhi(pv.x); o2 += bflo(pv.y); o3 += bfhi(pv.y);
;           }
;           uint2 w;
;           w.x = pack2(o0, o1); w.y = pack2(o2, o3);
;           *(uint2*)(MP + (size_t)tok * 2048 + cb) = w;
	v_mov_b32_e32 v64, v188
	v_mov_b32_e32 v65, v189
	v_addc_co_u32_e32 v57, vcc, 0, v57, vcc
	v_lshlrev_b32_e32 v60, 16, v86
	v_and_b32_e32 v61, 0xffff0000, v86
	v_lshlrev_b32_e32 v66, 16, v87
	v_and_b32_e32 v67, 0xffff0000, v87
	v_lshlrev_b32_e32 v68, 16, v64
	v_and_b32_e32 v69, 0xffff0000, v64
	v_lshlrev_b32_e32 v64, 16, v65
	v_and_b32_e32 v65, 0xffff0000, v65
	v_pk_fma_f32 v[48:49], v[48:49], v[68:69], v[60:61]
	v_pk_fma_f32 v[52:53], v[52:53], v[64:65], v[66:67]
	v_cvt_pk_bf16_f32 v48, v48, v49
	v_cvt_pk_bf16_f32 v49, v52, v53
	global_store_dwordx2 v[74:75], v[48:49], off
	s_waitcnt vmcnt(28)
	v_mov_b32_e32 v48, v190
	v_mov_b32_e32 v49, v191
	v_lshlrev_b64 v[60:61], 13, v[78:79]
	v_mov_b32_e32 v52, v58
	v_mov_b32_e32 v53, v50
	v_mov_b32_e32 v56, v62
	v_mov_b32_e32 v57, v54
	v_lshl_add_u64 v[60:61], s[28:29], 0, v[60:61]
	v_lshlrev_b32_e32 v64, 16, v88
	v_and_b32_e32 v65, 0xffff0000, v88
	v_lshlrev_b32_e32 v66, 16, v89
	v_and_b32_e32 v67, 0xffff0000, v89
	v_lshl_add_u64 v[60:61], v[60:61], 0, v[130:131]
	v_add_co_u32_e32 v60, vcc, s91, v60
	v_mov_b32_e32 v50, v59
	s_nop 0
	v_addc_co_u32_e32 v61, vcc, 0, v61, vcc
	v_mov_b32_e32 v54, v63
	v_lshlrev_b32_e32 v58, 16, v90
	v_and_b32_e32 v59, 0xffff0000, v90
	v_lshlrev_b32_e32 v68, 16, v48
	v_and_b32_e32 v69, 0xffff0000, v48
	v_lshlrev_b32_e32 v48, 16, v49
	v_and_b32_e32 v49, 0xffff0000, v49
	v_pk_fma_f32 v[52:53], v[52:53], v[68:69], v[64:65]
	v_pk_fma_f32 v[48:49], v[56:57], v[48:49], v[66:67]
	v_cvt_pk_bf16_f32 v52, v52, v53
	v_cvt_pk_bf16_f32 v53, v48, v49
	global_store_dwordx2 v[82:83], v[52:53], off
	s_waitcnt vmcnt(28)
	v_mov_b32_e32 v48, v192
	v_mov_b32_e32 v49, v193
	v_add_u32_e32 v52, 0x90, v134
	v_ashrrev_i32_e32 v53, 31, v52
	v_lshlrev_b64 v[56:57], 13, v[52:53]
	v_lshlrev_b32_e32 v60, 16, v91
	v_and_b32_e32 v61, 0xffff0000, v91
	v_lshl_add_u64 v[56:57], s[28:29], 0, v[56:57]
	v_lshl_add_u64 v[56:57], v[56:57], 0, v[130:131]
	v_add_co_u32_e32 v56, vcc, s91, v56
	v_lshlrev_b32_e32 v62, 16, v48
	v_and_b32_e32 v63, 0xffff0000, v48
	v_lshlrev_b32_e32 v48, 16, v49
	v_and_b32_e32 v49, 0xffff0000, v49
	v_pk_fma_f32 v[50:51], v[50:51], v[62:63], v[58:59]
	v_pk_fma_f32 v[48:49], v[54:55], v[48:49], v[60:61]
	v_cvt_pk_bf16_f32 v50, v50, v51
	v_cvt_pk_bf16_f32 v51, v48, v49
	global_store_dwordx2 v[84:85], v[50:51], off
	v_lshlrev_b64 v[50:51], 12, v[52:53]
	v_addc_co_u32_e32 v57, vcc, 0, v57, vcc
	v_lshl_add_u64 v[50:51], v[132:133], 0, v[50:51]
	s_waitcnt vmcnt(28)
	v_mov_b32_e32 v48, v194
	v_mov_b32_e32 v49, v195
	s_waitcnt vmcnt(27)
	v_mov_b32_e32 v52, v196
	v_mov_b32_e32 v53, v197
	v_add_u32_e32 v58, 0x91, v134
	v_ashrrev_i32_e32 v59, 31, v58
	v_lshlrev_b64 v[64:65], 13, v[58:59]
	v_mov_b32_e32 v54, v40
	v_mov_b32_e32 v55, v32
	v_mov_b32_e32 v56, v44
	v_mov_b32_e32 v57, v36
	v_add_u32_e32 v60, 0x92, v134
	v_add_u32_e32 v62, 0x93, v134
	v_lshl_add_u64 v[64:65], s[28:29], 0, v[64:65]
	v_ashrrev_i32_e32 v61, 31, v60
	v_ashrrev_i32_e32 v63, 31, v62
	v_lshlrev_b64 v[58:59], 12, v[58:59]
	v_lshl_add_u64 v[64:65], v[64:65], 0, v[130:131]
	v_lshlrev_b64 v[66:67], 12, v[60:61]
	v_lshlrev_b64 v[68:69], 12, v[62:63]
	v_lshl_add_u64 v[58:59], v[132:133], 0, v[58:59]
	v_add_co_u32_e32 v64, vcc, s91, v64
	v_lshl_add_u64 v[66:67], v[132:133], 0, v[66:67]
	v_lshl_add_u64 v[68:69], v[132:133], 0, v[68:69]
	v_addc_co_u32_e32 v65, vcc, 0, v65, vcc
	s_waitcnt vmcnt(26)
	v_mov_b32_e32 v70, v198
	v_mov_b32_e32 v71, v199
	s_waitcnt vmcnt(25)
	v_mov_b32_e32 v72, v200
	v_mov_b32_e32 v73, v201
	s_waitcnt vmcnt(24)
	v_mov_b32_e32 v74, v202
	v_mov_b32_e32 v75, v203
	v_mov_b32_e32 v32, v41
	v_lshlrev_b64 v[40:41], 13, v[60:61]
	v_mov_b32_e32 v36, v45
	v_lshl_add_u64 v[40:41], s[28:29], 0, v[40:41]
	v_lshl_add_u64 v[40:41], v[40:41], 0, v[130:131]
	v_add_co_u32_e32 v40, vcc, s91, v40
	v_lshlrev_b32_e32 v76, 16, v48
	v_and_b32_e32 v77, 0xffff0000, v48
	v_lshlrev_b32_e32 v48, 16, v49
	v_and_b32_e32 v49, 0xffff0000, v49
	v_lshlrev_b32_e32 v78, 16, v52
	v_and_b32_e32 v79, 0xffff0000, v52
	v_lshlrev_b32_e32 v52, 16, v53
	v_and_b32_e32 v53, 0xffff0000, v53
	v_pk_fma_f32 v[54:55], v[54:55], v[76:77], v[78:79]
	v_pk_fma_f32 v[48:49], v[56:57], v[48:49], v[52:53]
	v_cvt_pk_bf16_f32 v52, v54, v55
	v_cvt_pk_bf16_f32 v53, v48, v49
	global_store_dwordx2 v[50:51], v[52:53], off
	s_waitcnt vmcnt(24)
	v_mov_b32_e32 v48, v204
	v_mov_b32_e32 v49, v205
	v_addc_co_u32_e32 v41, vcc, 0, v41, vcc
	v_lshlrev_b32_e32 v44, 16, v70
	v_and_b32_e32 v45, 0xffff0000, v70
	v_lshlrev_b32_e32 v50, 16, v71
	v_and_b32_e32 v51, 0xffff0000, v71
	v_lshlrev_b32_e32 v52, 16, v48
	v_and_b32_e32 v53, 0xffff0000, v48
	v_lshlrev_b32_e32 v48, 16, v49
	v_and_b32_e32 v49, 0xffff0000, v49
	v_pk_fma_f32 v[32:33], v[32:33], v[52:53], v[44:45]
	v_pk_fma_f32 v[36:37], v[36:37], v[48:49], v[50:51]
	v_cvt_pk_bf16_f32 v32, v32, v33
	v_cvt_pk_bf16_f32 v33, v36, v37
	global_store_dwordx2 v[58:59], v[32:33], off
	s_waitcnt vmcnt(24)
	v_mov_b32_e32 v32, v206
	v_mov_b32_e32 v33, v207
	v_lshlrev_b64 v[44:45], 13, v[62:63]
	v_mov_b32_e32 v36, v42
	v_mov_b32_e32 v37, v34
	v_mov_b32_e32 v40, v46
	v_mov_b32_e32 v41, v38
	v_lshl_add_u64 v[44:45], s[28:29], 0, v[44:45]
	v_lshlrev_b32_e32 v48, 16, v72
	v_and_b32_e32 v49, 0xffff0000, v72
	v_lshlrev_b32_e32 v50, 16, v73
	v_and_b32_e32 v51, 0xffff0000, v73
	v_lshl_add_u64 v[44:45], v[44:45], 0, v[130:131]
	v_add_co_u32_e32 v44, vcc, s91, v44
	v_mov_b32_e32 v34, v43
	s_nop 0
	v_addc_co_u32_e32 v45, vcc, 0, v45, vcc
	v_mov_b32_e32 v38, v47
	v_lshlrev_b32_e32 v42, 16, v74
	v_and_b32_e32 v43, 0xffff0000, v74
	v_lshlrev_b32_e32 v52, 16, v32
	v_and_b32_e32 v53, 0xffff0000, v32
	v_lshlrev_b32_e32 v32, 16, v33
	v_and_b32_e32 v33, 0xffff0000, v33
	v_pk_fma_f32 v[36:37], v[36:37], v[52:53], v[48:49]
	v_pk_fma_f32 v[32:33], v[40:41], v[32:33], v[50:51]
	v_cvt_pk_bf16_f32 v36, v36, v37
	v_cvt_pk_bf16_f32 v37, v32, v33
	global_store_dwordx2 v[66:67], v[36:37], off
	s_waitcnt vmcnt(24)
; __device__ __forceinline__ float bflo(unsigned u) { return __uint_as_float(u << 16); }
; __device__ __forceinline__ float bfhi(unsigned u) { return __uint_as_float(u & 0xffff0000u); }
; #define EPI_FENCE(j) do { if ((j) == 0) asm volatile("" ::: "memory"); } while (0)
; template <int PASS>
; __device__ __forceinline__ void gemm3_pass(const Params& p, int wid_s, char* shm) {
;     ...
;         for (int j = 0; j < 4; ++j) { EPI_FENCE(j);
;           int tok = tokbase + ai * 128 + m * 16 + j;
;           uint2 g = *(const uint2*)(G + (size_t)tok * 4096 + (PASS == 0 ? 0 : 2048) + cb);
;           float o0 = bflo(g.x) * acc[ai][0][m][0][j], o1 = bfhi(g.x) * acc[ai][0][m][1][j];
;           float o2 = bflo(g.y) * acc[ai][1][m][0][j], o3 = bfhi(g.y) * acc[ai][1][m][1][j];
;           if (PASS == 1) {
;             uint2 pv = *(const uint2*)(MP + (size_t)tok * 2048 + cb);
;             o0 += bflo(pv.x); o1 += bfhi(pv.x); o2 += bflo(pv.y); o3 += bfhi(pv.y);
;           }
;           uint2 w;
;           w.x = pack2(o0, o1); w.y = pack2(o2, o3);
;           *(uint2*)(MP + (size_t)tok * 2048 + cb) = w;
	v_mov_b32_e32 v32, v208
	v_mov_b32_e32 v33, v209
	v_add_u32_e32 v36, 0xa0, v134
	v_ashrrev_i32_e32 v37, 31, v36
	v_lshlrev_b64 v[40:41], 13, v[36:37]
	v_lshlrev_b32_e32 v44, 16, v75
	v_and_b32_e32 v45, 0xffff0000, v75
	v_lshl_add_u64 v[40:41], s[28:29], 0, v[40:41]
	v_lshl_add_u64 v[40:41], v[40:41], 0, v[130:131]
	v_add_co_u32_e32 v40, vcc, s91, v40
	v_lshlrev_b32_e32 v46, 16, v32
	v_and_b32_e32 v47, 0xffff0000, v32
	v_lshlrev_b32_e32 v32, 16, v33
	v_and_b32_e32 v33, 0xffff0000, v33
	v_pk_fma_f32 v[34:35], v[34:35], v[46:47], v[42:43]
	v_pk_fma_f32 v[32:33], v[38:39], v[32:33], v[44:45]
	v_cvt_pk_bf16_f32 v34, v34, v35
	v_cvt_pk_bf16_f32 v35, v32, v33
	global_store_dwordx2 v[68:69], v[34:35], off
	v_lshlrev_b64 v[34:35], 12, v[36:37]
	v_addc_co_u32_e32 v41, vcc, 0, v41, vcc
	v_lshl_add_u64 v[34:35], v[132:133], 0, v[34:35]
	s_waitcnt vmcnt(24)
	v_mov_b32_e32 v32, v210
	v_mov_b32_e32 v33, v211
	s_waitcnt vmcnt(23)
	v_mov_b32_e32 v36, v212
	v_mov_b32_e32 v37, v213
	v_add_u32_e32 v42, 0xa1, v134
	v_ashrrev_i32_e32 v43, 31, v42
	v_lshlrev_b64 v[48:49], 13, v[42:43]
	v_mov_b32_e32 v38, v24
	v_mov_b32_e32 v39, v16
	v_mov_b32_e32 v40, v28
	v_mov_b32_e32 v41, v20
	v_add_u32_e32 v44, 0xa2, v134
	v_add_u32_e32 v46, 0xa3, v134
	v_lshl_add_u64 v[48:49], s[28:29], 0, v[48:49]
	v_ashrrev_i32_e32 v45, 31, v44
	v_ashrrev_i32_e32 v47, 31, v46
	v_lshlrev_b64 v[42:43], 12, v[42:43]
	v_lshl_add_u64 v[48:49], v[48:49], 0, v[130:131]
	v_lshlrev_b64 v[50:51], 12, v[44:45]
	v_lshlrev_b64 v[52:53], 12, v[46:47]
	v_lshl_add_u64 v[42:43], v[132:133], 0, v[42:43]
	v_add_co_u32_e32 v48, vcc, s91, v48
	v_lshl_add_u64 v[50:51], v[132:133], 0, v[50:51]
	v_lshl_add_u64 v[52:53], v[132:133], 0, v[52:53]
	v_addc_co_u32_e32 v49, vcc, 0, v49, vcc
	s_waitcnt vmcnt(22)
	v_mov_b32_e32 v54, v214
	v_mov_b32_e32 v55, v215
	s_waitcnt vmcnt(21)
	v_mov_b32_e32 v56, v216
	v_mov_b32_e32 v57, v217
	s_waitcnt vmcnt(20)
	v_mov_b32_e32 v58, v218
	v_mov_b32_e32 v59, v219
	v_mov_b32_e32 v16, v25
	v_lshlrev_b64 v[24:25], 13, v[44:45]
	v_mov_b32_e32 v20, v29
	v_lshl_add_u64 v[24:25], s[28:29], 0, v[24:25]
	v_lshl_add_u64 v[24:25], v[24:25], 0, v[130:131]
	v_add_co_u32_e32 v24, vcc, s91, v24
	v_lshlrev_b32_e32 v60, 16, v32
	v_and_b32_e32 v61, 0xffff0000, v32
	v_lshlrev_b32_e32 v32, 16, v33
	v_and_b32_e32 v33, 0xffff0000, v33
	v_lshlrev_b32_e32 v62, 16, v36
	v_and_b32_e32 v63, 0xffff0000, v36
	v_lshlrev_b32_e32 v36, 16, v37
	v_and_b32_e32 v37, 0xffff0000, v37
	v_pk_fma_f32 v[38:39], v[38:39], v[60:61], v[62:63]
	v_pk_fma_f32 v[32:33], v[40:41], v[32:33], v[36:37]
	v_cvt_pk_bf16_f32 v36, v38, v39
	v_cvt_pk_bf16_f32 v37, v32, v33
	global_store_dwordx2 v[34:35], v[36:37], off
	s_waitcnt vmcnt(20)
	v_mov_b32_e32 v32, v220
	v_mov_b32_e32 v33, v221
	v_addc_co_u32_e32 v25, vcc, 0, v25, vcc
	v_lshlrev_b32_e32 v28, 16, v54
	v_and_b32_e32 v29, 0xffff0000, v54
	v_lshlrev_b32_e32 v34, 16, v55
	v_and_b32_e32 v35, 0xffff0000, v55
	v_lshlrev_b32_e32 v36, 16, v32
	v_and_b32_e32 v37, 0xffff0000, v32
	v_lshlrev_b32_e32 v32, 16, v33
	v_and_b32_e32 v33, 0xffff0000, v33
	v_pk_fma_f32 v[16:17], v[16:17], v[36:37], v[28:29]
	v_pk_fma_f32 v[20:21], v[20:21], v[32:33], v[34:35]
	v_cvt_pk_bf16_f32 v16, v16, v17
	v_cvt_pk_bf16_f32 v17, v20, v21
	global_store_dwordx2 v[42:43], v[16:17], off
	s_waitcnt vmcnt(20)
	v_mov_b32_e32 v16, v222
	v_mov_b32_e32 v17, v223
	v_lshlrev_b64 v[28:29], 13, v[46:47]
	v_mov_b32_e32 v20, v26
	v_mov_b32_e32 v21, v18
	v_mov_b32_e32 v24, v30
	v_mov_b32_e32 v25, v22
	v_lshl_add_u64 v[28:29], s[28:29], 0, v[28:29]
	v_lshlrev_b32_e32 v32, 16, v56
	v_and_b32_e32 v33, 0xffff0000, v56
	v_lshlrev_b32_e32 v34, 16, v57
	v_and_b32_e32 v35, 0xffff0000, v57
	v_lshl_add_u64 v[28:29], v[28:29], 0, v[130:131]
	v_add_co_u32_e32 v28, vcc, s91, v28
	v_mov_b32_e32 v18, v27
	s_nop 0
	v_addc_co_u32_e32 v29, vcc, 0, v29, vcc
	v_mov_b32_e32 v22, v31
	v_lshlrev_b32_e32 v26, 16, v58
	v_and_b32_e32 v27, 0xffff0000, v58
	v_lshlrev_b32_e32 v36, 16, v16
	v_and_b32_e32 v37, 0xffff0000, v16
	v_lshlrev_b32_e32 v16, 16, v17
	v_and_b32_e32 v17, 0xffff0000, v17
	v_pk_fma_f32 v[20:21], v[20:21], v[36:37], v[32:33]
	v_pk_fma_f32 v[16:17], v[24:25], v[16:17], v[34:35]
	v_cvt_pk_bf16_f32 v20, v20, v21
	v_cvt_pk_bf16_f32 v21, v16, v17
	global_store_dwordx2 v[50:51], v[20:21], off
	s_waitcnt vmcnt(20)
; __device__ __forceinline__ float bflo(unsigned u) { return __uint_as_float(u << 16); }
; __device__ __forceinline__ float bfhi(unsigned u) { return __uint_as_float(u & 0xffff0000u); }
; #define EPI_FENCE(j) do { if ((j) == 0) asm volatile("" ::: "memory"); } while (0)
; template <int PASS>
; __device__ __forceinline__ void gemm3_pass(const Params& p, int wid_s, char* shm) {
;     ...
;         for (int j = 0; j < 4; ++j) { EPI_FENCE(j);
;           int tok = tokbase + ai * 128 + m * 16 + j;
;           uint2 g = *(const uint2*)(G + (size_t)tok * 4096 + (PASS == 0 ? 0 : 2048) + cb);
;           float o0 = bflo(g.x) * acc[ai][0][m][0][j], o1 = bfhi(g.x) * acc[ai][0][m][1][j];
;           float o2 = bflo(g.y) * acc[ai][1][m][0][j], o3 = bfhi(g.y) * acc[ai][1][m][1][j];
;           if (PASS == 1) {
;             uint2 pv = *(const uint2*)(MP + (size_t)tok * 2048 + cb);
;             o0 += bflo(pv.x); o1 += bfhi(pv.x); o2 += bflo(pv.y); o3 += bfhi(pv.y);
;           }
;           uint2 w;
;           w.x = pack2(o0, o1); w.y = pack2(o2, o3);
;           *(uint2*)(MP + (size_t)tok * 2048 + cb) = w;
	v_mov_b32_e32 v16, v224
	v_mov_b32_e32 v17, v225
	v_add_u32_e32 v20, 0xb0, v134
	v_ashrrev_i32_e32 v21, 31, v20
	v_lshlrev_b64 v[24:25], 13, v[20:21]
	v_lshlrev_b32_e32 v28, 16, v59
	v_and_b32_e32 v29, 0xffff0000, v59
	v_lshl_add_u64 v[24:25], s[28:29], 0, v[24:25]
	v_lshl_add_u64 v[24:25], v[24:25], 0, v[130:131]
	v_add_co_u32_e32 v24, vcc, s91, v24
	v_lshlrev_b32_e32 v30, 16, v16
	v_and_b32_e32 v31, 0xffff0000, v16
	v_lshlrev_b32_e32 v16, 16, v17
	v_and_b32_e32 v17, 0xffff0000, v17
	v_pk_fma_f32 v[18:19], v[18:19], v[30:31], v[26:27]
	v_pk_fma_f32 v[16:17], v[22:23], v[16:17], v[28:29]
	v_cvt_pk_bf16_f32 v18, v18, v19
	v_cvt_pk_bf16_f32 v19, v16, v17
	global_store_dwordx2 v[52:53], v[18:19], off
	v_lshlrev_b64 v[18:19], 12, v[20:21]
	v_addc_co_u32_e32 v25, vcc, 0, v25, vcc
	v_lshl_add_u64 v[18:19], v[132:133], 0, v[18:19]
	s_waitcnt vmcnt(20)
	v_mov_b32_e32 v16, v226
	v_mov_b32_e32 v17, v227
	s_waitcnt vmcnt(19)
	v_mov_b32_e32 v20, v228
	v_mov_b32_e32 v21, v229
	v_add_u32_e32 v26, 0xb1, v134
	v_ashrrev_i32_e32 v27, 31, v26
	v_lshlrev_b64 v[32:33], 13, v[26:27]
	v_mov_b32_e32 v22, v8
	v_mov_b32_e32 v23, v0
	v_mov_b32_e32 v24, v12
	v_mov_b32_e32 v25, v4
	v_add_u32_e32 v28, 0xb2, v134
	v_add_u32_e32 v30, 0xb3, v134
	v_lshl_add_u64 v[32:33], s[28:29], 0, v[32:33]
	v_ashrrev_i32_e32 v29, 31, v28
	v_ashrrev_i32_e32 v31, 31, v30
	v_lshlrev_b64 v[26:27], 12, v[26:27]
	v_lshl_add_u64 v[32:33], v[32:33], 0, v[130:131]
	v_lshlrev_b64 v[34:35], 12, v[28:29]
	v_lshlrev_b64 v[36:37], 12, v[30:31]
	v_lshl_add_u64 v[26:27], v[132:133], 0, v[26:27]
	v_add_co_u32_e32 v32, vcc, s91, v32
	v_lshl_add_u64 v[34:35], v[132:133], 0, v[34:35]
	v_lshl_add_u64 v[36:37], v[132:133], 0, v[36:37]
	v_addc_co_u32_e32 v33, vcc, 0, v33, vcc
	s_waitcnt vmcnt(18)
	v_mov_b32_e32 v38, v230
	v_mov_b32_e32 v39, v231
	s_waitcnt vmcnt(17)
	v_mov_b32_e32 v40, v232
	v_mov_b32_e32 v41, v233
	s_waitcnt vmcnt(16)
	v_mov_b32_e32 v42, v234
	v_mov_b32_e32 v43, v235
	v_mov_b32_e32 v0, v9
	v_lshlrev_b64 v[8:9], 13, v[28:29]
	v_mov_b32_e32 v4, v13
	v_lshl_add_u64 v[8:9], s[28:29], 0, v[8:9]
	v_lshl_add_u64 v[8:9], v[8:9], 0, v[130:131]
	v_add_co_u32_e32 v8, vcc, s91, v8
	v_lshlrev_b32_e32 v44, 16, v16
	v_and_b32_e32 v45, 0xffff0000, v16
	v_lshlrev_b32_e32 v16, 16, v17
	v_and_b32_e32 v17, 0xffff0000, v17
	v_lshlrev_b32_e32 v46, 16, v20
	v_and_b32_e32 v47, 0xffff0000, v20
	v_lshlrev_b32_e32 v20, 16, v21
	v_and_b32_e32 v21, 0xffff0000, v21
	v_pk_fma_f32 v[22:23], v[22:23], v[44:45], v[46:47]
	v_pk_fma_f32 v[16:17], v[24:25], v[16:17], v[20:21]
	v_cvt_pk_bf16_f32 v20, v22, v23
	v_cvt_pk_bf16_f32 v21, v16, v17
	global_store_dwordx2 v[18:19], v[20:21], off
	s_waitcnt vmcnt(16)
	v_mov_b32_e32 v16, v236
	v_mov_b32_e32 v17, v237
	v_addc_co_u32_e32 v9, vcc, 0, v9, vcc
	v_lshlrev_b32_e32 v12, 16, v38
	v_and_b32_e32 v13, 0xffff0000, v38
	v_lshlrev_b32_e32 v18, 16, v39
	v_and_b32_e32 v19, 0xffff0000, v39
	v_lshlrev_b32_e32 v20, 16, v16
	v_and_b32_e32 v21, 0xffff0000, v16
	v_lshlrev_b32_e32 v16, 16, v17
	v_and_b32_e32 v17, 0xffff0000, v17
	v_pk_fma_f32 v[0:1], v[0:1], v[20:21], v[12:13]
	v_pk_fma_f32 v[4:5], v[4:5], v[16:17], v[18:19]
	v_cvt_pk_bf16_f32 v0, v0, v1
	v_cvt_pk_bf16_f32 v1, v4, v5
	global_store_dwordx2 v[26:27], v[0:1], off
	s_waitcnt vmcnt(16)
	v_mov_b32_e32 v0, v238
	v_mov_b32_e32 v1, v239
	v_lshlrev_b64 v[12:13], 13, v[30:31]
	v_mov_b32_e32 v4, v10
	v_mov_b32_e32 v5, v2
	v_mov_b32_e32 v8, v14
	v_mov_b32_e32 v9, v6
	v_lshl_add_u64 v[12:13], s[28:29], 0, v[12:13]
	v_lshlrev_b32_e32 v16, 16, v40
	v_and_b32_e32 v17, 0xffff0000, v40
	v_lshlrev_b32_e32 v18, 16, v41
	v_and_b32_e32 v19, 0xffff0000, v41
	v_lshl_add_u64 v[12:13], v[12:13], 0, v[130:131]
	v_add_co_u32_e32 v12, vcc, s91, v12
	v_mov_b32_e32 v2, v11
	s_nop 0
	v_addc_co_u32_e32 v13, vcc, 0, v13, vcc
	v_mov_b32_e32 v6, v15
	v_lshlrev_b32_e32 v20, 16, v0
	v_and_b32_e32 v21, 0xffff0000, v0
	v_lshlrev_b32_e32 v0, 16, v1
	v_and_b32_e32 v1, 0xffff0000, v1
	v_pk_fma_f32 v[4:5], v[4:5], v[20:21], v[16:17]
	v_pk_fma_f32 v[0:1], v[8:9], v[0:1], v[18:19]
	v_cvt_pk_bf16_f32 v4, v4, v5
	v_cvt_pk_bf16_f32 v5, v0, v1
	global_store_dwordx2 v[34:35], v[4:5], off
	s_waitcnt vmcnt(16)
	v_mov_b32_e32 v0, v240
	v_mov_b32_e32 v1, v241
	v_lshlrev_b32_e32 v4, 16, v42
	v_and_b32_e32 v5, 0xffff0000, v42
	v_lshlrev_b32_e32 v8, 16, v43
	v_and_b32_e32 v9, 0xffff0000, v43
	v_lshlrev_b32_e32 v10, 16, v0
	v_and_b32_e32 v11, 0xffff0000, v0
	v_lshlrev_b32_e32 v0, 16, v1
	v_and_b32_e32 v1, 0xffff0000, v1
	v_pk_fma_f32 v[2:3], v[2:3], v[10:11], v[4:5]
	v_pk_fma_f32 v[0:1], v[6:7], v[0:1], v[8:9]
	v_cvt_pk_bf16_f32 v2, v2, v3
	v_cvt_pk_bf16_f32 v3, v0, v1
	global_store_dwordx2 v[36:37], v[2:3], off

; __global__ void __launch_bounds__(512) fwd_mega(Params p) {
;   __shared__ __attribute__((aligned(1024))) char shm[136 * 1024];
;   cg::grid_group grid = cg::this_grid();
;   const int wid_s = __builtin_amdgcn_readfirstlane((int)(threadIdx.x >> 6));
	.amdhsa_kernel _Z8fwd_mega6Params
		.amdhsa_group_segment_fixed_size 139264
		.amdhsa_private_segment_fixed_size 0
		.amdhsa_kernarg_size 520
		.amdhsa_user_sgpr_count 2
		.amdhsa_user_sgpr_dispatch_ptr 0
		.amdhsa_user_sgpr_queue_ptr 0
		.amdhsa_user_sgpr_kernarg_segment_ptr 1
		.amdhsa_user_sgpr_dispatch_id 0
		.amdhsa_user_sgpr_kernarg_preload_length 0
		.amdhsa_user_sgpr_kernarg_preload_offset 0
		.amdhsa_user_sgpr_private_segment_size 0
		.amdhsa_uses_dynamic_stack 0
		.amdhsa_enable_private_segment 0
		.amdhsa_system_sgpr_workgroup_id_x 1
		.amdhsa_system_sgpr_workgroup_id_y 0
		.amdhsa_system_sgpr_workgroup_id_z 0
		.amdhsa_system_sgpr_workgroup_info 0
		.amdhsa_system_vgpr_workitem_id 2
		.amdhsa_next_free_vgpr 255
		.amdhsa_next_free_sgpr 102
		.amdhsa_accum_offset 256
		.amdhsa_reserve_vcc 1
		.amdhsa_float_round_mode_32 0
		.amdhsa_float_round_mode_16_64 0
		.amdhsa_float_denorm_mode_32 3
		.amdhsa_float_denorm_mode_16_64 3
		.amdhsa_dx10_clamp 1
		.amdhsa_ieee_mode 1
		.amdhsa_fp16_overflow 0
		.amdhsa_tg_split 0
		.amdhsa_exception_fp_ieee_invalid_op 0
		.amdhsa_exception_fp_denorm_src 0
		.amdhsa_exception_fp_ieee_div_zero 0
		.amdhsa_exception_fp_ieee_overflow 0
		.amdhsa_exception_fp_ieee_underflow 0
		.amdhsa_exception_fp_ieee_inexact 0
		.amdhsa_exception_int_div_zero 0
	.end_amdhsa_kernel

; __global__ void __launch_bounds__(512) fwd_mega(Params p) {
;   __shared__ __attribute__((aligned(1024))) char shm[136 * 1024];
;   cg::grid_group grid = cg::this_grid();
;   const int wid_s = __builtin_amdgcn_readfirstlane((int)(threadIdx.x >> 6));
amdhsa.kernels:
  - .agpr_count:     0
    .args:
      - .offset:         0
        .size:           264
        .value_kind:     by_value
      - .offset:         264
        .size:           4
        .value_kind:     hidden_block_count_x
      - .offset:         268
        .size:           4
        .value_kind:     hidden_block_count_y
      - .offset:         272
        .size:           4
        .value_kind:     hidden_block_count_z
      - .offset:         276
        .size:           2
        .value_kind:     hidden_group_size_x
      - .offset:         278
        .size:           2
        .value_kind:     hidden_group_size_y
      - .offset:         280
        .size:           2
        .value_kind:     hidden_group_size_z
      - .offset:         282
        .size:           2
        .value_kind:     hidden_remainder_x
      - .offset:         284
        .size:           2
        .value_kind:     hidden_remainder_y
      - .offset:         286
        .size:           2
        .value_kind:     hidden_remainder_z
      - .offset:         304
        .size:           8
        .value_kind:     hidden_global_offset_x
      - .offset:         312
        .size:           8
        .value_kind:     hidden_global_offset_y
      - .offset:         320
        .size:           8
        .value_kind:     hidden_global_offset_z
      - .offset:         328
        .size:           2
        .value_kind:     hidden_grid_dims
      - .offset:         352
        .size:           8
        .value_kind:     hidden_multigrid_sync_arg
    .group_segment_fixed_size: 139264
    .kernarg_segment_align: 8
    .kernarg_segment_size: 520
    .language:       OpenCL C
    .language_version:
      - 2
      - 0
    .max_flat_workgroup_size: 512
    .name:           _Z8fwd_mega6Params
    .private_segment_fixed_size: 0
    .sgpr_count:     108
    .sgpr_spill_count: 52
    .symbol:         _Z8fwd_mega6Params.kd
    .uniform_work_group_size: 1
    .uses_dynamic_stack: false
    .vgpr_count:     255
    .vgpr_spill_count: 0
    .wavefront_size: 64
